# v39 + the same accumulator-zeroing removal (first K iteration peeled, first-touch MFMAs take C=0) in the other six GEMM K loops
# baseline (speedup 1.0000x reference)
.LBB0_338:
	s_add_u32 s53, s28, 0x100
	s_addc_u32 s54, s29, 0
	s_mov_b32 s55, -2
	s_add_u32 s6, s26, 0x100
	s_addc_u32 s7, s27, 0
	s_add_i32 s56, 0, 0x10000
	s_cmp_eq_u32 s55, 40
	s_cselect_b32 s31, s23, s7
	s_cselect_b32 s30, s22, s6
	s_cselect_b32 s29, s25, s54
	s_cselect_b32 s28, s24, s53
	s_add_i32 s57, 0, 0x14000
	v_add_u32_e32 v106, s56, v254
	v_add_u32_e32 v150, s57, v254
	ds_read_b128 v[72:75], v106
	ds_read_b128 v[84:87], v106 offset:1024
	ds_read_b128 v[98:101], v106 offset:2048
	ds_read_b128 v[106:109], v106 offset:3072
	ds_read_b128 v[122:125], v150
	ds_read_b128 v[126:129], v150 offset:1024
	ds_read_b128 v[142:145], v150 offset:2048
	ds_read_b128 v[150:153], v150 offset:3072
	v_lshl_add_u64 v[194:195], s[26:27], 0, v[208:209]
	s_add_i32 m0, s40, 0xc000
	ds_read_b128 v[162:165], v198
	ds_read_b128 v[166:169], v198 offset:1024
	ds_read_b128 v[170:173], v198 offset:2048
	ds_read_b128 v[174:177], v198 offset:3072
	ds_read_b128 v[178:181], v198 offset:4096
	ds_read_b128 v[182:185], v198 offset:5120
	ds_read_b128 v[186:189], v198 offset:6144
	ds_read_b128 v[190:193], v198 offset:7168
	global_load_lds_dwordx4 v[194:195], off
	v_lshl_add_u64 v[194:195], s[26:27], 0, v[210:211]
	s_add_i32 m0, s40, 0xe000
	s_nop 0
	global_load_lds_dwordx4 v[194:195], off
	s_waitcnt vmcnt(8)
	s_waitcnt lgkmcnt(0)
	s_barrier
	s_setprio 1
	s_waitcnt lgkmcnt(0)
	v_mfma_f32_16x16x32_bf16 v[158:161], v[72:75], v[162:165], 0
	v_mfma_f32_16x16x32_bf16 v[154:157], v[98:101], v[162:165], 0
	v_mfma_f32_16x16x32_bf16 v[134:137], v[72:75], v[170:173], 0
	v_mfma_f32_16x16x32_bf16 v[130:133], v[98:101], v[170:173], 0
	v_mfma_f32_16x16x32_bf16 v[110:113], v[72:75], v[178:181], 0
	v_mfma_f32_16x16x32_bf16 v[102:105], v[98:101], v[178:181], 0
	v_mfma_f32_16x16x32_bf16 v[80:83], v[72:75], v[186:189], 0
	v_mfma_f32_16x16x32_bf16 v[76:79], v[98:101], v[186:189], 0
	v_mfma_f32_16x16x32_bf16 v[158:161], v[84:87], v[166:169], v[158:161]
	v_mfma_f32_16x16x32_bf16 v[154:157], v[106:109], v[166:169], v[154:157]
	v_mfma_f32_16x16x32_bf16 v[134:137], v[84:87], v[174:177], v[134:137]
	v_mfma_f32_16x16x32_bf16 v[130:133], v[106:109], v[174:177], v[130:133]
	v_mfma_f32_16x16x32_bf16 v[110:113], v[84:87], v[182:185], v[110:113]
	v_mfma_f32_16x16x32_bf16 v[102:105], v[106:109], v[182:185], v[102:105]
	v_mfma_f32_16x16x32_bf16 v[80:83], v[84:87], v[190:193], v[80:83]
	v_mfma_f32_16x16x32_bf16 v[76:79], v[106:109], v[190:193], v[76:79]
	s_setprio 0
	s_setprio 1
	v_mfma_f32_16x16x32_bf16 v[146:149], v[122:125], v[162:165], 0
	v_mfma_f32_16x16x32_bf16 v[138:141], v[142:145], v[162:165], 0
	v_mfma_f32_16x16x32_bf16 v[118:121], v[122:125], v[170:173], 0
	v_mfma_f32_16x16x32_bf16 v[114:117], v[142:145], v[170:173], 0
	v_mfma_f32_16x16x32_bf16 v[92:95], v[122:125], v[178:181], 0
	v_mfma_f32_16x16x32_bf16 v[88:91], v[142:145], v[178:181], 0
	v_mfma_f32_16x16x32_bf16 v[68:71], v[122:125], v[186:189], 0
	v_mfma_f32_16x16x32_bf16 v[64:67], v[142:145], v[186:189], 0
	v_mfma_f32_16x16x32_bf16 v[146:149], v[126:129], v[166:169], v[146:149]
	v_mfma_f32_16x16x32_bf16 v[138:141], v[150:153], v[166:169], v[138:141]
	v_mfma_f32_16x16x32_bf16 v[118:121], v[126:129], v[174:177], v[118:121]
	v_mfma_f32_16x16x32_bf16 v[114:117], v[150:153], v[174:177], v[114:117]
	v_mfma_f32_16x16x32_bf16 v[92:95], v[126:129], v[182:185], v[92:95]
	v_mfma_f32_16x16x32_bf16 v[88:91], v[150:153], v[182:185], v[88:91]
	v_mfma_f32_16x16x32_bf16 v[68:71], v[126:129], v[190:193], v[68:71]
	v_mfma_f32_16x16x32_bf16 v[64:67], v[150:153], v[190:193], v[64:67]
	s_setprio 0
	s_barrier
	s_add_i32 s26, s56, s39
	v_lshl_add_u64 v[194:195], s[28:29], 0, v[96:97]
	s_mov_b32 m0, s26
	ds_read_b128 v[162:165], v198 offset:16384
	ds_read_b128 v[166:169], v198 offset:17408
	ds_read_b128 v[170:173], v198 offset:18432
	ds_read_b128 v[174:177], v198 offset:19456
	ds_read_b128 v[178:181], v198 offset:20480
	ds_read_b128 v[182:185], v198 offset:21504
	ds_read_b128 v[186:189], v198 offset:22528
	ds_read_b128 v[190:193], v198 offset:23552
	global_load_lds_dwordx4 v[194:195], off
	s_add_i32 m0, s26, 0x2000
	s_add_u32 s26, s28, 0xb0000
	v_lshl_add_u64 v[196:197], s[28:29], 0, v[206:207]
	s_addc_u32 s27, s29, 0
	s_add_i32 s56, s57, s39
	global_load_lds_dwordx4 v[196:197], off
	v_lshl_add_u64 v[200:201], s[26:27], 0, v[96:97]
	s_mov_b32 m0, s56
	v_lshl_add_u64 v[212:213], s[30:31], 0, v[204:205]
	global_load_lds_dwordx4 v[200:201], off
	v_lshl_add_u64 v[200:201], s[26:27], 0, v[206:207]
	s_add_i32 m0, s56, 0x2000
	s_nop 0
	global_load_lds_dwordx4 v[200:201], off
	v_lshl_add_u64 v[200:201], s[30:31], 0, v[202:203]
	s_mov_b32 m0, s40
	s_nop 0
	global_load_lds_dwordx4 v[200:201], off
	s_mov_b32 m0, s41
	s_nop 0
	global_load_lds_dwordx4 v[212:213], off
	s_waitcnt vmcnt(8)
	s_waitcnt lgkmcnt(0)
	s_barrier
	s_setprio 1
	s_waitcnt lgkmcnt(0)
	v_mfma_f32_16x16x32_bf16 v[60:63], v[72:75], v[162:165], 0
	v_mfma_f32_16x16x32_bf16 v[56:59], v[98:101], v[162:165], 0
	v_mfma_f32_16x16x32_bf16 v[44:47], v[72:75], v[170:173], 0
	v_mfma_f32_16x16x32_bf16 v[40:43], v[98:101], v[170:173], 0
	v_mfma_f32_16x16x32_bf16 v[28:31], v[72:75], v[178:181], 0
	v_mfma_f32_16x16x32_bf16 v[24:27], v[98:101], v[178:181], 0
	v_mfma_f32_16x16x32_bf16 v[12:15], v[72:75], v[186:189], 0
	v_mfma_f32_16x16x32_bf16 v[8:11], v[98:101], v[186:189], 0
	v_mfma_f32_16x16x32_bf16 v[60:63], v[84:87], v[166:169], v[60:63]
	v_mfma_f32_16x16x32_bf16 v[56:59], v[106:109], v[166:169], v[56:59]
	v_mfma_f32_16x16x32_bf16 v[44:47], v[84:87], v[174:177], v[44:47]
	v_mfma_f32_16x16x32_bf16 v[40:43], v[106:109], v[174:177], v[40:43]
	v_mfma_f32_16x16x32_bf16 v[28:31], v[84:87], v[182:185], v[28:31]
	v_mfma_f32_16x16x32_bf16 v[24:27], v[106:109], v[182:185], v[24:27]
	v_mfma_f32_16x16x32_bf16 v[12:15], v[84:87], v[190:193], v[12:15]
	v_mfma_f32_16x16x32_bf16 v[8:11], v[106:109], v[190:193], v[8:11]
	s_setprio 0
	s_setprio 1
	v_mfma_f32_16x16x32_bf16 v[52:55], v[122:125], v[162:165], 0
	v_mfma_f32_16x16x32_bf16 v[48:51], v[142:145], v[162:165], 0
	v_mfma_f32_16x16x32_bf16 v[36:39], v[122:125], v[170:173], 0
	v_mfma_f32_16x16x32_bf16 v[32:35], v[142:145], v[170:173], 0
	v_mfma_f32_16x16x32_bf16 v[20:23], v[122:125], v[178:181], 0
	v_mfma_f32_16x16x32_bf16 v[16:19], v[142:145], v[178:181], 0
	v_mfma_f32_16x16x32_bf16 v[4:7], v[122:125], v[186:189], 0
	v_mfma_f32_16x16x32_bf16 v[0:3], v[142:145], v[186:189], 0
	v_mfma_f32_16x16x32_bf16 v[52:55], v[126:129], v[166:169], v[52:55]
	v_mfma_f32_16x16x32_bf16 v[48:51], v[150:153], v[166:169], v[48:51]
	v_mfma_f32_16x16x32_bf16 v[36:39], v[126:129], v[174:177], v[36:39]
	v_mfma_f32_16x16x32_bf16 v[32:35], v[150:153], v[174:177], v[32:35]
	v_mfma_f32_16x16x32_bf16 v[20:23], v[126:129], v[182:185], v[20:23]
	v_mfma_f32_16x16x32_bf16 v[16:19], v[150:153], v[182:185], v[16:19]
	v_mfma_f32_16x16x32_bf16 v[4:7], v[126:129], v[190:193], v[4:7]
	v_mfma_f32_16x16x32_bf16 v[0:3], v[150:153], v[190:193], v[0:3]
	s_setprio 0
	s_barrier
	s_add_i32 s56, 0, 0x18000
	s_add_i32 s57, 0, 0x1c000
	v_add_u32_e32 v106, s56, v254
	v_add_u32_e32 v150, s57, v254
	ds_read_b128 v[72:75], v106
	ds_read_b128 v[84:87], v106 offset:1024
	ds_read_b128 v[98:101], v106 offset:2048
	ds_read_b128 v[106:109], v106 offset:3072
	ds_read_b128 v[122:125], v150
	ds_read_b128 v[126:129], v150 offset:1024
	ds_read_b128 v[142:145], v150 offset:2048
	ds_read_b128 v[150:153], v150 offset:3072
	s_add_u32 s26, s30, 0xb0000
	s_addc_u32 s27, s31, 0
	s_mov_b32 m0, s42
	v_lshl_add_u64 v[214:215], s[26:27], 0, v[202:203]
	ds_read_b128 v[162:165], v198 offset:32768
	ds_read_b128 v[166:169], v198 offset:33792
	ds_read_b128 v[170:173], v198 offset:34816
	ds_read_b128 v[174:177], v198 offset:35840
	ds_read_b128 v[178:181], v198 offset:36864
	ds_read_b128 v[182:185], v198 offset:37888
	ds_read_b128 v[186:189], v198 offset:38912
	ds_read_b128 v[190:193], v198 offset:39936
	global_load_lds_dwordx4 v[214:215], off
	v_lshl_add_u64 v[214:215], s[26:27], 0, v[204:205]
	s_mov_b32 m0, s43
	s_nop 0
	global_load_lds_dwordx4 v[214:215], off
	s_waitcnt vmcnt(8)
	s_waitcnt lgkmcnt(0)
	s_barrier
	s_setprio 1
	s_waitcnt lgkmcnt(0)
	v_mfma_f32_16x16x32_bf16 v[158:161], v[72:75], v[162:165], v[158:161]
	v_mfma_f32_16x16x32_bf16 v[154:157], v[98:101], v[162:165], v[154:157]
	v_mfma_f32_16x16x32_bf16 v[134:137], v[72:75], v[170:173], v[134:137]
	v_mfma_f32_16x16x32_bf16 v[130:133], v[98:101], v[170:173], v[130:133]
	v_mfma_f32_16x16x32_bf16 v[110:113], v[72:75], v[178:181], v[110:113]
	v_mfma_f32_16x16x32_bf16 v[102:105], v[98:101], v[178:181], v[102:105]
	v_mfma_f32_16x16x32_bf16 v[80:83], v[72:75], v[186:189], v[80:83]
	v_mfma_f32_16x16x32_bf16 v[76:79], v[98:101], v[186:189], v[76:79]
	v_mfma_f32_16x16x32_bf16 v[158:161], v[84:87], v[166:169], v[158:161]
	v_mfma_f32_16x16x32_bf16 v[154:157], v[106:109], v[166:169], v[154:157]
	v_mfma_f32_16x16x32_bf16 v[134:137], v[84:87], v[174:177], v[134:137]
	v_mfma_f32_16x16x32_bf16 v[130:133], v[106:109], v[174:177], v[130:133]
	v_mfma_f32_16x16x32_bf16 v[110:113], v[84:87], v[182:185], v[110:113]
	v_mfma_f32_16x16x32_bf16 v[102:105], v[106:109], v[182:185], v[102:105]
	v_mfma_f32_16x16x32_bf16 v[80:83], v[84:87], v[190:193], v[80:83]
	v_mfma_f32_16x16x32_bf16 v[76:79], v[106:109], v[190:193], v[76:79]
	s_setprio 0
	s_setprio 1
	v_mfma_f32_16x16x32_bf16 v[146:149], v[122:125], v[162:165], v[146:149]
	v_mfma_f32_16x16x32_bf16 v[138:141], v[142:145], v[162:165], v[138:141]
	v_mfma_f32_16x16x32_bf16 v[118:121], v[122:125], v[170:173], v[118:121]
	v_mfma_f32_16x16x32_bf16 v[114:117], v[142:145], v[170:173], v[114:117]
	v_mfma_f32_16x16x32_bf16 v[92:95], v[122:125], v[178:181], v[92:95]
	v_mfma_f32_16x16x32_bf16 v[88:91], v[142:145], v[178:181], v[88:91]
	v_mfma_f32_16x16x32_bf16 v[68:71], v[122:125], v[186:189], v[68:71]
	v_mfma_f32_16x16x32_bf16 v[64:67], v[142:145], v[186:189], v[64:67]
	v_mfma_f32_16x16x32_bf16 v[146:149], v[126:129], v[166:169], v[146:149]
	v_mfma_f32_16x16x32_bf16 v[138:141], v[150:153], v[166:169], v[138:141]
	v_mfma_f32_16x16x32_bf16 v[118:121], v[126:129], v[174:177], v[118:121]
	v_mfma_f32_16x16x32_bf16 v[114:117], v[150:153], v[174:177], v[114:117]
	v_mfma_f32_16x16x32_bf16 v[92:95], v[126:129], v[182:185], v[92:95]
	v_mfma_f32_16x16x32_bf16 v[88:91], v[150:153], v[182:185], v[88:91]
	v_mfma_f32_16x16x32_bf16 v[68:71], v[126:129], v[190:193], v[68:71]
	v_mfma_f32_16x16x32_bf16 v[64:67], v[150:153], v[190:193], v[64:67]
	s_setprio 0
	s_barrier
	s_add_i32 s26, s56, s39
	v_lshl_add_u64 v[194:195], v[194:195], 0, s[64:65]
	s_mov_b32 m0, s26
	ds_read_b128 v[162:165], v198 offset:49152
	ds_read_b128 v[166:169], v198 offset:50176
	ds_read_b128 v[170:173], v198 offset:51200
	ds_read_b128 v[174:177], v198 offset:52224
	ds_read_b128 v[178:181], v198 offset:53248
	ds_read_b128 v[182:185], v198 offset:54272
	ds_read_b128 v[186:189], v198 offset:55296
	ds_read_b128 v[190:193], v198 offset:56320
	global_load_lds_dwordx4 v[194:195], off
	s_add_i32 m0, s26, 0x2000
	s_add_u32 s26, s28, 0xb0080
	v_lshl_add_u64 v[194:195], v[196:197], 0, s[64:65]
	s_addc_u32 s27, s29, 0
	s_add_i32 s28, s57, s39
	global_load_lds_dwordx4 v[194:195], off
	v_lshl_add_u64 v[194:195], s[26:27], 0, v[96:97]
	s_mov_b32 m0, s28
	s_nop 0
	global_load_lds_dwordx4 v[194:195], off
	v_lshl_add_u64 v[194:195], s[26:27], 0, v[206:207]
	s_add_i32 m0, s28, 0x2000
	s_nop 0
	global_load_lds_dwordx4 v[194:195], off
	v_lshl_add_u64 v[194:195], v[200:201], 0, s[64:65]
	s_mov_b32 m0, s45
	s_nop 0
	global_load_lds_dwordx4 v[194:195], off
	v_lshl_add_u64 v[194:195], v[212:213], 0, s[64:65]
	s_mov_b32 m0, s46
	s_nop 0
	global_load_lds_dwordx4 v[194:195], off
	s_waitcnt vmcnt(8)
	s_waitcnt lgkmcnt(0)
	s_barrier
	s_setprio 1
	s_waitcnt lgkmcnt(0)
	v_mfma_f32_16x16x32_bf16 v[60:63], v[72:75], v[162:165], v[60:63]
	v_mfma_f32_16x16x32_bf16 v[56:59], v[98:101], v[162:165], v[56:59]
	v_mfma_f32_16x16x32_bf16 v[44:47], v[72:75], v[170:173], v[44:47]
	v_mfma_f32_16x16x32_bf16 v[40:43], v[98:101], v[170:173], v[40:43]
	v_mfma_f32_16x16x32_bf16 v[28:31], v[72:75], v[178:181], v[28:31]
	v_mfma_f32_16x16x32_bf16 v[24:27], v[98:101], v[178:181], v[24:27]
	v_mfma_f32_16x16x32_bf16 v[12:15], v[72:75], v[186:189], v[12:15]
	v_mfma_f32_16x16x32_bf16 v[8:11], v[98:101], v[186:189], v[8:11]
	v_mfma_f32_16x16x32_bf16 v[60:63], v[84:87], v[166:169], v[60:63]
	v_mfma_f32_16x16x32_bf16 v[56:59], v[106:109], v[166:169], v[56:59]
	v_mfma_f32_16x16x32_bf16 v[44:47], v[84:87], v[174:177], v[44:47]
	v_mfma_f32_16x16x32_bf16 v[40:43], v[106:109], v[174:177], v[40:43]
	v_mfma_f32_16x16x32_bf16 v[28:31], v[84:87], v[182:185], v[28:31]
	v_mfma_f32_16x16x32_bf16 v[24:27], v[106:109], v[182:185], v[24:27]
	v_mfma_f32_16x16x32_bf16 v[12:15], v[84:87], v[190:193], v[12:15]
	v_mfma_f32_16x16x32_bf16 v[8:11], v[106:109], v[190:193], v[8:11]
	s_setprio 0
	s_setprio 1
	v_mfma_f32_16x16x32_bf16 v[52:55], v[122:125], v[162:165], v[52:55]
	v_mfma_f32_16x16x32_bf16 v[48:51], v[142:145], v[162:165], v[48:51]
	v_mfma_f32_16x16x32_bf16 v[36:39], v[122:125], v[170:173], v[36:39]
	v_mfma_f32_16x16x32_bf16 v[32:35], v[142:145], v[170:173], v[32:35]
	v_mfma_f32_16x16x32_bf16 v[20:23], v[122:125], v[178:181], v[20:23]
	v_mfma_f32_16x16x32_bf16 v[16:19], v[142:145], v[178:181], v[16:19]
	v_mfma_f32_16x16x32_bf16 v[4:7], v[122:125], v[186:189], v[4:7]
	v_mfma_f32_16x16x32_bf16 v[0:3], v[142:145], v[186:189], v[0:3]
	v_mfma_f32_16x16x32_bf16 v[52:55], v[126:129], v[166:169], v[52:55]
	v_mfma_f32_16x16x32_bf16 v[48:51], v[150:153], v[166:169], v[48:51]
	v_mfma_f32_16x16x32_bf16 v[36:39], v[126:129], v[174:177], v[36:39]
	v_mfma_f32_16x16x32_bf16 v[32:35], v[150:153], v[174:177], v[32:35]
	v_mfma_f32_16x16x32_bf16 v[20:23], v[126:129], v[182:185], v[20:23]
	v_mfma_f32_16x16x32_bf16 v[16:19], v[150:153], v[182:185], v[16:19]
	v_mfma_f32_16x16x32_bf16 v[4:7], v[126:129], v[190:193], v[4:7]
	v_mfma_f32_16x16x32_bf16 v[0:3], v[150:153], v[190:193], v[0:3]
	s_setprio 0
	s_barrier
	s_add_i32 s55, s55, 2
	s_add_u32 s53, s53, 0x100
	s_addc_u32 s54, s54, 0
	s_cmp_gt_u32 s55, 41
	s_mov_b64 s[26:27], s[6:7]
	s_cbranch_scc1 .Lpeel_done_339

.Lpeel_done_339:
	s_and_b64 vcc, exec, s[18:19]
	s_cbranch_vccz .LBB0_342
	s_barrier

.LBB0_460:
	s_ashr_i32 s21, s20, 31
	s_lshl_b64 s[22:23], s[20:21], 19
	s_add_u32 s22, s40, s22
	s_addc_u32 s23, s41, s23
	s_and_b64 s[24:25], s[2:3], exec
	s_cselect_b32 s21, s23, s29
	s_cselect_b32 s51, s22, s28
	s_ashr_i32 s19, s18, 31
	s_lshl_b64 s[24:25], s[18:19], 19
	s_add_u32 s24, s38, s24
	s_addc_u32 s25, s39, s25
	s_and_b64 s[34:35], s[2:3], exec
	s_cselect_b32 s19, s25, s31
	s_cselect_b32 s52, s24, s30
	s_add_u32 s28, s28, 0x40080
	s_addc_u32 s29, s29, 0
	s_add_u32 s53, s30, 0x100
	s_addc_u32 s54, s31, 0
	s_mov_b32 s55, -2
	s_add_u32 s30, s28, 0xfffc0080
	s_addc_u32 s31, s29, -1
	s_add_i32 s56, 0, 0x10000
	s_cmp_eq_u32 s55, 12
	s_cselect_b32 s35, s21, s31
	s_cselect_b32 s34, s51, s30
	v_add_u32_e32 v96, s56, v148
	s_cselect_b32 s31, s19, s54
	s_cselect_b32 s30, s52, s53
	s_add_i32 s60, 0, 0x14000
	ds_read_b128 v[144:147], v96
	ds_read_b128 v[154:157], v96 offset:1024
	ds_read_b128 v[158:161], v96 offset:2048
	ds_read_b128 v[162:165], v96 offset:3072
	v_add_u32_e32 v96, s60, v148
	ds_read_b128 v[166:169], v96
	ds_read_b128 v[170:173], v96 offset:1024
	ds_read_b128 v[174:177], v96 offset:2048
	ds_read_b128 v[178:181], v96 offset:3072
	v_lshl_add_u64 v[214:215], s[28:29], 0, v[140:141]
	s_add_i32 m0, s43, 0xc000
	ds_read_b128 v[182:185], v152
	ds_read_b128 v[186:189], v152 offset:1024
	ds_read_b128 v[190:193], v152 offset:2048
	ds_read_b128 v[194:197], v152 offset:3072
	ds_read_b128 v[198:201], v152 offset:4096
	ds_read_b128 v[202:205], v152 offset:5120
	ds_read_b128 v[206:209], v152 offset:6144
	ds_read_b128 v[210:213], v152 offset:7168
	global_load_lds_dwordx4 v[214:215], off
	v_lshl_add_u64 v[214:215], s[28:29], 0, v[142:143]
	s_add_i32 m0, s43, 0xe000
	s_nop 0
	global_load_lds_dwordx4 v[214:215], off
	s_waitcnt vmcnt(8)
	s_waitcnt lgkmcnt(0)
	s_barrier
	s_setprio 1
	s_waitcnt lgkmcnt(0)
	v_mfma_f32_16x16x32_bf16 v[122:125], v[144:147], v[182:185], 0
	v_mfma_f32_16x16x32_bf16 v[126:129], v[158:161], v[182:185], 0
	v_mfma_f32_16x16x32_bf16 v[106:109], v[144:147], v[190:193], 0
	v_mfma_f32_16x16x32_bf16 v[110:113], v[158:161], v[190:193], 0
	v_mfma_f32_16x16x32_bf16 v[88:91], v[144:147], v[198:201], 0
	v_mfma_f32_16x16x32_bf16 v[92:95], v[158:161], v[198:201], 0
	v_mfma_f32_16x16x32_bf16 v[72:75], v[144:147], v[206:209], 0
	v_mfma_f32_16x16x32_bf16 v[76:79], v[158:161], v[206:209], 0
	v_mfma_f32_16x16x32_bf16 v[122:125], v[154:157], v[186:189], v[122:125]
	v_mfma_f32_16x16x32_bf16 v[126:129], v[162:165], v[186:189], v[126:129]
	v_mfma_f32_16x16x32_bf16 v[106:109], v[154:157], v[194:197], v[106:109]
	v_mfma_f32_16x16x32_bf16 v[110:113], v[162:165], v[194:197], v[110:113]
	v_mfma_f32_16x16x32_bf16 v[88:91], v[154:157], v[202:205], v[88:91]
	v_mfma_f32_16x16x32_bf16 v[92:95], v[162:165], v[202:205], v[92:95]
	v_mfma_f32_16x16x32_bf16 v[72:75], v[154:157], v[210:213], v[72:75]
	v_mfma_f32_16x16x32_bf16 v[76:79], v[162:165], v[210:213], v[76:79]
	s_setprio 0
	s_setprio 1
	v_mfma_f32_16x16x32_bf16 v[118:121], v[166:169], v[182:185], 0
	v_mfma_f32_16x16x32_bf16 v[114:117], v[174:177], v[182:185], 0
	v_mfma_f32_16x16x32_bf16 v[102:105], v[166:169], v[190:193], 0
	v_mfma_f32_16x16x32_bf16 v[98:101], v[174:177], v[190:193], 0
	v_mfma_f32_16x16x32_bf16 v[84:87], v[166:169], v[198:201], 0
	v_mfma_f32_16x16x32_bf16 v[80:83], v[174:177], v[198:201], 0
	v_mfma_f32_16x16x32_bf16 v[68:71], v[166:169], v[206:209], 0
	v_mfma_f32_16x16x32_bf16 v[64:67], v[174:177], v[206:209], 0
	v_mfma_f32_16x16x32_bf16 v[118:121], v[170:173], v[186:189], v[118:121]
	v_mfma_f32_16x16x32_bf16 v[114:117], v[178:181], v[186:189], v[114:117]
	v_mfma_f32_16x16x32_bf16 v[102:105], v[170:173], v[194:197], v[102:105]
	v_mfma_f32_16x16x32_bf16 v[98:101], v[178:181], v[194:197], v[98:101]
	v_mfma_f32_16x16x32_bf16 v[84:87], v[170:173], v[202:205], v[84:87]
	v_mfma_f32_16x16x32_bf16 v[80:83], v[178:181], v[202:205], v[80:83]
	v_mfma_f32_16x16x32_bf16 v[68:71], v[170:173], v[210:213], v[68:71]
	v_mfma_f32_16x16x32_bf16 v[64:67], v[178:181], v[210:213], v[64:67]
	s_setprio 0
	s_barrier
	s_add_i32 s56, s56, s42
	v_lshl_add_u64 v[214:215], s[30:31], 0, v[132:133]
	s_mov_b32 m0, s56
	ds_read_b128 v[182:185], v152 offset:16384
	ds_read_b128 v[186:189], v152 offset:17408
	ds_read_b128 v[190:193], v152 offset:18432
	ds_read_b128 v[194:197], v152 offset:19456
	ds_read_b128 v[198:201], v152 offset:20480
	ds_read_b128 v[202:205], v152 offset:21504
	ds_read_b128 v[206:209], v152 offset:22528
	ds_read_b128 v[210:213], v152 offset:23552
	global_load_lds_dwordx4 v[214:215], off
	s_add_i32 m0, s56, 0x2000
	s_add_u32 s56, s30, 0x40000
	v_lshl_add_u64 v[216:217], s[30:31], 0, v[136:137]
	s_addc_u32 s57, s31, 0
	s_add_i32 s60, s60, s42
	global_load_lds_dwordx4 v[216:217], off
	v_lshl_add_u64 v[218:219], s[56:57], 0, v[132:133]
	s_mov_b32 m0, s60
	v_lshl_add_u64 v[220:221], s[34:35], 0, v[134:135]
	global_load_lds_dwordx4 v[218:219], off
	v_lshl_add_u64 v[218:219], s[56:57], 0, v[136:137]
	s_add_i32 m0, s60, 0x2000
	s_nop 0
	global_load_lds_dwordx4 v[218:219], off
	v_lshl_add_u64 v[218:219], s[34:35], 0, v[130:131]
	s_mov_b32 m0, s43
	s_nop 0
	global_load_lds_dwordx4 v[218:219], off
	s_mov_b32 m0, s44
	s_nop 0
	global_load_lds_dwordx4 v[220:221], off
	s_waitcnt vmcnt(8)
	s_waitcnt lgkmcnt(0)
	s_barrier
	s_setprio 1
	s_waitcnt lgkmcnt(0)
	v_mfma_f32_16x16x32_bf16 v[56:59], v[144:147], v[182:185], 0
	v_mfma_f32_16x16x32_bf16 v[60:63], v[158:161], v[182:185], 0
	v_mfma_f32_16x16x32_bf16 v[40:43], v[144:147], v[190:193], 0
	v_mfma_f32_16x16x32_bf16 v[44:47], v[158:161], v[190:193], 0
	v_mfma_f32_16x16x32_bf16 v[24:27], v[144:147], v[198:201], 0
	v_mfma_f32_16x16x32_bf16 v[28:31], v[158:161], v[198:201], 0
	v_mfma_f32_16x16x32_bf16 v[8:11], v[144:147], v[206:209], 0
	v_mfma_f32_16x16x32_bf16 v[12:15], v[158:161], v[206:209], 0
	v_mfma_f32_16x16x32_bf16 v[56:59], v[154:157], v[186:189], v[56:59]
	v_mfma_f32_16x16x32_bf16 v[60:63], v[162:165], v[186:189], v[60:63]
	v_mfma_f32_16x16x32_bf16 v[40:43], v[154:157], v[194:197], v[40:43]
	v_mfma_f32_16x16x32_bf16 v[44:47], v[162:165], v[194:197], v[44:47]
	v_mfma_f32_16x16x32_bf16 v[24:27], v[154:157], v[202:205], v[24:27]
	v_mfma_f32_16x16x32_bf16 v[28:31], v[162:165], v[202:205], v[28:31]
	v_mfma_f32_16x16x32_bf16 v[8:11], v[154:157], v[210:213], v[8:11]
	v_mfma_f32_16x16x32_bf16 v[12:15], v[162:165], v[210:213], v[12:15]
	s_setprio 0
	s_setprio 1
	v_mfma_f32_16x16x32_bf16 v[52:55], v[166:169], v[182:185], 0
	v_mfma_f32_16x16x32_bf16 v[48:51], v[174:177], v[182:185], 0
	v_mfma_f32_16x16x32_bf16 v[36:39], v[166:169], v[190:193], 0
	v_mfma_f32_16x16x32_bf16 v[32:35], v[174:177], v[190:193], 0
	v_mfma_f32_16x16x32_bf16 v[20:23], v[166:169], v[198:201], 0
	v_mfma_f32_16x16x32_bf16 v[16:19], v[174:177], v[198:201], 0
	v_mfma_f32_16x16x32_bf16 v[4:7], v[166:169], v[206:209], 0
	v_mfma_f32_16x16x32_bf16 v[0:3], v[174:177], v[206:209], 0
	v_mfma_f32_16x16x32_bf16 v[52:55], v[170:173], v[186:189], v[52:55]
	v_mfma_f32_16x16x32_bf16 v[48:51], v[178:181], v[186:189], v[48:51]
	v_mfma_f32_16x16x32_bf16 v[36:39], v[170:173], v[194:197], v[36:39]
	v_mfma_f32_16x16x32_bf16 v[32:35], v[178:181], v[194:197], v[32:35]
	v_mfma_f32_16x16x32_bf16 v[20:23], v[170:173], v[202:205], v[20:23]
	v_mfma_f32_16x16x32_bf16 v[16:19], v[178:181], v[202:205], v[16:19]
	v_mfma_f32_16x16x32_bf16 v[4:7], v[170:173], v[210:213], v[4:7]
	v_mfma_f32_16x16x32_bf16 v[0:3], v[178:181], v[210:213], v[0:3]
	s_setprio 0
	s_barrier
	s_add_i32 s56, 0, 0x18000
	v_add_u32_e32 v96, s56, v148
	s_add_i32 s57, 0, 0x1c000
	ds_read_b128 v[144:147], v96
	ds_read_b128 v[154:157], v96 offset:1024
	ds_read_b128 v[158:161], v96 offset:2048
	ds_read_b128 v[162:165], v96 offset:3072
	v_add_u32_e32 v96, s57, v148
	ds_read_b128 v[166:169], v96
	ds_read_b128 v[170:173], v96 offset:1024
	ds_read_b128 v[174:177], v96 offset:2048
	ds_read_b128 v[178:181], v96 offset:3072
	s_add_u32 s34, s34, 0x40000
	s_addc_u32 s35, s35, 0
	s_mov_b32 m0, s45
	v_lshl_add_u64 v[222:223], s[34:35], 0, v[130:131]
	ds_read_b128 v[182:185], v152 offset:32768
	ds_read_b128 v[186:189], v152 offset:33792
	ds_read_b128 v[190:193], v152 offset:34816
	ds_read_b128 v[194:197], v152 offset:35840
	ds_read_b128 v[198:201], v152 offset:36864
	ds_read_b128 v[202:205], v152 offset:37888
	ds_read_b128 v[206:209], v152 offset:38912
	ds_read_b128 v[210:213], v152 offset:39936
	global_load_lds_dwordx4 v[222:223], off
	v_lshl_add_u64 v[222:223], s[34:35], 0, v[134:135]
	s_mov_b32 m0, s46
	s_nop 0
	global_load_lds_dwordx4 v[222:223], off
	s_waitcnt vmcnt(8)
	s_waitcnt lgkmcnt(0)
	s_barrier
	s_setprio 1
	s_waitcnt lgkmcnt(0)
	v_mfma_f32_16x16x32_bf16 v[122:125], v[144:147], v[182:185], v[122:125]
	v_mfma_f32_16x16x32_bf16 v[126:129], v[158:161], v[182:185], v[126:129]
	v_mfma_f32_16x16x32_bf16 v[106:109], v[144:147], v[190:193], v[106:109]
	v_mfma_f32_16x16x32_bf16 v[110:113], v[158:161], v[190:193], v[110:113]
	v_mfma_f32_16x16x32_bf16 v[88:91], v[144:147], v[198:201], v[88:91]
	v_mfma_f32_16x16x32_bf16 v[92:95], v[158:161], v[198:201], v[92:95]
	v_mfma_f32_16x16x32_bf16 v[72:75], v[144:147], v[206:209], v[72:75]
	v_mfma_f32_16x16x32_bf16 v[76:79], v[158:161], v[206:209], v[76:79]
	v_mfma_f32_16x16x32_bf16 v[122:125], v[154:157], v[186:189], v[122:125]
	v_mfma_f32_16x16x32_bf16 v[126:129], v[162:165], v[186:189], v[126:129]
	v_mfma_f32_16x16x32_bf16 v[106:109], v[154:157], v[194:197], v[106:109]
	v_mfma_f32_16x16x32_bf16 v[110:113], v[162:165], v[194:197], v[110:113]
	v_mfma_f32_16x16x32_bf16 v[88:91], v[154:157], v[202:205], v[88:91]
	v_mfma_f32_16x16x32_bf16 v[92:95], v[162:165], v[202:205], v[92:95]
	v_mfma_f32_16x16x32_bf16 v[72:75], v[154:157], v[210:213], v[72:75]
	v_mfma_f32_16x16x32_bf16 v[76:79], v[162:165], v[210:213], v[76:79]
	s_setprio 0
	s_setprio 1
	v_mfma_f32_16x16x32_bf16 v[118:121], v[166:169], v[182:185], v[118:121]
	v_mfma_f32_16x16x32_bf16 v[114:117], v[174:177], v[182:185], v[114:117]
	v_mfma_f32_16x16x32_bf16 v[102:105], v[166:169], v[190:193], v[102:105]
	v_mfma_f32_16x16x32_bf16 v[98:101], v[174:177], v[190:193], v[98:101]
	v_mfma_f32_16x16x32_bf16 v[84:87], v[166:169], v[198:201], v[84:87]
	v_mfma_f32_16x16x32_bf16 v[80:83], v[174:177], v[198:201], v[80:83]
	v_mfma_f32_16x16x32_bf16 v[68:71], v[166:169], v[206:209], v[68:71]
	v_mfma_f32_16x16x32_bf16 v[64:67], v[174:177], v[206:209], v[64:67]
	v_mfma_f32_16x16x32_bf16 v[118:121], v[170:173], v[186:189], v[118:121]
	v_mfma_f32_16x16x32_bf16 v[114:117], v[178:181], v[186:189], v[114:117]
	v_mfma_f32_16x16x32_bf16 v[102:105], v[170:173], v[194:197], v[102:105]
	v_mfma_f32_16x16x32_bf16 v[98:101], v[178:181], v[194:197], v[98:101]
	v_mfma_f32_16x16x32_bf16 v[84:87], v[170:173], v[202:205], v[84:87]
	v_mfma_f32_16x16x32_bf16 v[80:83], v[178:181], v[202:205], v[80:83]
	v_mfma_f32_16x16x32_bf16 v[68:71], v[170:173], v[210:213], v[68:71]
	v_mfma_f32_16x16x32_bf16 v[64:67], v[178:181], v[210:213], v[64:67]
	s_setprio 0
	s_barrier
	s_add_i32 s34, s56, s42
	v_lshl_add_u64 v[214:215], v[214:215], 0, s[64:65]
	s_mov_b32 m0, s34
	ds_read_b128 v[182:185], v152 offset:49152
	ds_read_b128 v[186:189], v152 offset:50176
	ds_read_b128 v[190:193], v152 offset:51200
	ds_read_b128 v[194:197], v152 offset:52224
	ds_read_b128 v[198:201], v152 offset:53248
	ds_read_b128 v[202:205], v152 offset:54272
	ds_read_b128 v[206:209], v152 offset:55296
	ds_read_b128 v[210:213], v152 offset:56320
	global_load_lds_dwordx4 v[214:215], off
	s_add_i32 m0, s34, 0x2000
	s_add_u32 s30, s30, 0x40080
	v_lshl_add_u64 v[214:215], v[216:217], 0, s[64:65]
	s_addc_u32 s31, s31, 0
	s_add_i32 s34, s57, s42
	global_load_lds_dwordx4 v[214:215], off
	v_lshl_add_u64 v[214:215], s[30:31], 0, v[132:133]
	s_mov_b32 m0, s34
	s_nop 0
	global_load_lds_dwordx4 v[214:215], off
	v_lshl_add_u64 v[214:215], s[30:31], 0, v[136:137]
	s_add_i32 m0, s34, 0x2000
	s_nop 0
	global_load_lds_dwordx4 v[214:215], off
	v_lshl_add_u64 v[214:215], v[218:219], 0, s[64:65]
	s_mov_b32 m0, s48
	s_nop 0
	global_load_lds_dwordx4 v[214:215], off
	v_lshl_add_u64 v[214:215], v[220:221], 0, s[64:65]
	s_mov_b32 m0, s49
	s_nop 0
	global_load_lds_dwordx4 v[214:215], off
	s_waitcnt vmcnt(8)
	s_waitcnt lgkmcnt(0)
	s_barrier
	s_setprio 1
	s_waitcnt lgkmcnt(0)
	v_mfma_f32_16x16x32_bf16 v[56:59], v[144:147], v[182:185], v[56:59]
	v_mfma_f32_16x16x32_bf16 v[60:63], v[158:161], v[182:185], v[60:63]
	v_mfma_f32_16x16x32_bf16 v[40:43], v[144:147], v[190:193], v[40:43]
	v_mfma_f32_16x16x32_bf16 v[44:47], v[158:161], v[190:193], v[44:47]
	v_mfma_f32_16x16x32_bf16 v[24:27], v[144:147], v[198:201], v[24:27]
	v_mfma_f32_16x16x32_bf16 v[28:31], v[158:161], v[198:201], v[28:31]
	v_mfma_f32_16x16x32_bf16 v[8:11], v[144:147], v[206:209], v[8:11]
	v_mfma_f32_16x16x32_bf16 v[12:15], v[158:161], v[206:209], v[12:15]
	v_mfma_f32_16x16x32_bf16 v[56:59], v[154:157], v[186:189], v[56:59]
	v_mfma_f32_16x16x32_bf16 v[60:63], v[162:165], v[186:189], v[60:63]
	v_mfma_f32_16x16x32_bf16 v[40:43], v[154:157], v[194:197], v[40:43]
	v_mfma_f32_16x16x32_bf16 v[44:47], v[162:165], v[194:197], v[44:47]
	v_mfma_f32_16x16x32_bf16 v[24:27], v[154:157], v[202:205], v[24:27]
	v_mfma_f32_16x16x32_bf16 v[28:31], v[162:165], v[202:205], v[28:31]
	v_mfma_f32_16x16x32_bf16 v[8:11], v[154:157], v[210:213], v[8:11]
	v_mfma_f32_16x16x32_bf16 v[12:15], v[162:165], v[210:213], v[12:15]
	s_setprio 0
	s_setprio 1
	v_mfma_f32_16x16x32_bf16 v[52:55], v[166:169], v[182:185], v[52:55]
	v_mfma_f32_16x16x32_bf16 v[48:51], v[174:177], v[182:185], v[48:51]
	v_mfma_f32_16x16x32_bf16 v[36:39], v[166:169], v[190:193], v[36:39]
	v_mfma_f32_16x16x32_bf16 v[32:35], v[174:177], v[190:193], v[32:35]
	v_mfma_f32_16x16x32_bf16 v[20:23], v[166:169], v[198:201], v[20:23]
	v_mfma_f32_16x16x32_bf16 v[16:19], v[174:177], v[198:201], v[16:19]
	v_mfma_f32_16x16x32_bf16 v[4:7], v[166:169], v[206:209], v[4:7]
	v_mfma_f32_16x16x32_bf16 v[0:3], v[174:177], v[206:209], v[0:3]
	v_mfma_f32_16x16x32_bf16 v[52:55], v[170:173], v[186:189], v[52:55]
	v_mfma_f32_16x16x32_bf16 v[48:51], v[178:181], v[186:189], v[48:51]
	v_mfma_f32_16x16x32_bf16 v[36:39], v[170:173], v[194:197], v[36:39]
	v_mfma_f32_16x16x32_bf16 v[32:35], v[178:181], v[194:197], v[32:35]
	v_mfma_f32_16x16x32_bf16 v[20:23], v[170:173], v[202:205], v[20:23]
	v_mfma_f32_16x16x32_bf16 v[16:19], v[178:181], v[202:205], v[16:19]
	v_mfma_f32_16x16x32_bf16 v[4:7], v[170:173], v[210:213], v[4:7]
	v_mfma_f32_16x16x32_bf16 v[0:3], v[178:181], v[210:213], v[0:3]
	s_setprio 0
	s_barrier
	s_add_i32 s55, s55, 2
	s_add_u32 s28, s28, 0x100
	s_addc_u32 s29, s29, 0
	s_add_u32 s53, s53, 0x100
	s_addc_u32 s54, s54, 0
	s_cmp_gt_u32 s55, 13
	s_cbranch_scc1 .Lpeel_done_461

.Lpeel_done_461:
	s_and_b64 vcc, exec, s[14:15]
	s_cbranch_vccz .LBB0_464
	s_barrier

.LBB0_633:
	s_ashr_i32 s17, s16, 31
	s_lshl_b64 s[18:19], s[16:17], 19
	s_add_u32 s18, s35, s18
	s_addc_u32 s19, s36, s19
	s_and_b64 s[20:21], s[4:5], exec
	s_cselect_b32 s17, s19, s27
	s_cselect_b32 s23, s18, s26
	s_ashr_i32 s15, s14, 31
	s_lshl_b64 s[20:21], s[14:15], 19
	s_add_u32 s20, s37, s20
	s_addc_u32 s21, s38, s21
	s_and_b64 s[30:31], s[4:5], exec
	s_cselect_b32 s15, s21, s29
	s_cselect_b32 s25, s20, s28
	s_add_u32 s26, s26, 0x40080
	s_addc_u32 s27, s27, 0
	s_add_u32 s49, s28, 0x100
	s_addc_u32 s50, s29, 0
	s_mov_b32 s51, -2
	s_add_u32 s28, s26, 0xfffc0080
	s_addc_u32 s29, s27, -1
	s_add_i32 s52, 0, 0x10000
	s_cmp_eq_u32 s51, 12
	s_cselect_b32 s31, s17, s29
	s_cselect_b32 s30, s23, s28
	s_cselect_b32 s29, s15, s50
	s_cselect_b32 s28, s25, s49
	s_add_i32 s54, 0, 0x14000
	v_add_u32_e32 v134, s52, v245
	v_add_u32_e32 v150, s54, v245
	ds_read_b128 v[122:125], v134
	ds_read_b128 v[126:129], v134 offset:1024
	ds_read_b128 v[130:133], v134 offset:2048
	ds_read_b128 v[134:137], v134 offset:3072
	ds_read_b128 v[138:141], v150
	ds_read_b128 v[142:145], v150 offset:1024
	ds_read_b128 v[146:149], v150 offset:2048
	ds_read_b128 v[150:153], v150 offset:3072
	v_lshl_add_u64 v[200:201], s[26:27], 0, v[204:205]
	s_add_i32 m0, s40, 0xc000
	ds_read_b128 v[162:165], v199
	ds_read_b128 v[166:169], v199 offset:1024
	ds_read_b128 v[170:173], v199 offset:2048
	ds_read_b128 v[174:177], v199 offset:3072
	ds_read_b128 v[178:181], v199 offset:4096
	ds_read_b128 v[182:185], v199 offset:5120
	ds_read_b128 v[186:189], v199 offset:6144
	ds_read_b128 v[194:197], v199 offset:7168
	global_load_lds_dwordx4 v[200:201], off
	v_lshl_add_u64 v[200:201], s[26:27], 0, v[206:207]
	s_add_i32 m0, s40, 0xe000
	s_nop 0
	global_load_lds_dwordx4 v[200:201], off
	s_waitcnt vmcnt(8)
	s_waitcnt lgkmcnt(0)
	s_barrier
	s_setprio 1
	s_waitcnt lgkmcnt(0)
	v_mfma_f32_16x16x32_bf16 v[158:161], v[122:125], v[162:165], 0
	v_mfma_f32_16x16x32_bf16 v[154:157], v[130:133], v[162:165], 0
	v_mfma_f32_16x16x32_bf16 v[110:113], v[122:125], v[170:173], 0
	v_mfma_f32_16x16x32_bf16 v[106:109], v[130:133], v[170:173], 0
	v_mfma_f32_16x16x32_bf16 v[92:95], v[122:125], v[178:181], 0
	v_mfma_f32_16x16x32_bf16 v[88:91], v[130:133], v[178:181], 0
	v_mfma_f32_16x16x32_bf16 v[76:79], v[122:125], v[186:189], 0
	v_mfma_f32_16x16x32_bf16 v[72:75], v[130:133], v[186:189], 0
	v_mfma_f32_16x16x32_bf16 v[158:161], v[126:129], v[166:169], v[158:161]
	v_mfma_f32_16x16x32_bf16 v[154:157], v[134:137], v[166:169], v[154:157]
	v_mfma_f32_16x16x32_bf16 v[110:113], v[126:129], v[174:177], v[110:113]
	v_mfma_f32_16x16x32_bf16 v[106:109], v[134:137], v[174:177], v[106:109]
	v_mfma_f32_16x16x32_bf16 v[92:95], v[126:129], v[182:185], v[92:95]
	v_mfma_f32_16x16x32_bf16 v[88:91], v[134:137], v[182:185], v[88:91]
	v_mfma_f32_16x16x32_bf16 v[76:79], v[126:129], v[194:197], v[76:79]
	v_mfma_f32_16x16x32_bf16 v[72:75], v[134:137], v[194:197], v[72:75]
	s_setprio 0
	s_setprio 1
	v_mfma_f32_16x16x32_bf16 v[118:121], v[138:141], v[162:165], 0
	v_mfma_f32_16x16x32_bf16 v[114:117], v[146:149], v[162:165], 0
	v_mfma_f32_16x16x32_bf16 v[102:105], v[138:141], v[170:173], 0
	v_mfma_f32_16x16x32_bf16 v[98:101], v[146:149], v[170:173], 0
	v_mfma_f32_16x16x32_bf16 v[84:87], v[138:141], v[178:181], 0
	v_mfma_f32_16x16x32_bf16 v[80:83], v[146:149], v[178:181], 0
	v_mfma_f32_16x16x32_bf16 v[68:71], v[138:141], v[186:189], 0
	v_mfma_f32_16x16x32_bf16 v[64:67], v[146:149], v[186:189], 0
	v_mfma_f32_16x16x32_bf16 v[118:121], v[142:145], v[166:169], v[118:121]
	v_mfma_f32_16x16x32_bf16 v[114:117], v[150:153], v[166:169], v[114:117]
	v_mfma_f32_16x16x32_bf16 v[102:105], v[142:145], v[174:177], v[102:105]
	v_mfma_f32_16x16x32_bf16 v[98:101], v[150:153], v[174:177], v[98:101]
	v_mfma_f32_16x16x32_bf16 v[84:87], v[142:145], v[182:185], v[84:87]
	v_mfma_f32_16x16x32_bf16 v[80:83], v[150:153], v[182:185], v[80:83]
	v_mfma_f32_16x16x32_bf16 v[68:71], v[142:145], v[194:197], v[68:71]
	v_mfma_f32_16x16x32_bf16 v[64:67], v[150:153], v[194:197], v[64:67]
	s_setprio 0
	s_barrier
	s_add_i32 s52, s52, s39
	v_lshl_add_u64 v[200:201], s[28:29], 0, v[96:97]
	s_mov_b32 m0, s52
	ds_read_b128 v[162:165], v199 offset:16384
	ds_read_b128 v[166:169], v199 offset:17408
	ds_read_b128 v[170:173], v199 offset:18432
	ds_read_b128 v[174:177], v199 offset:19456
	ds_read_b128 v[178:181], v199 offset:20480
	ds_read_b128 v[182:185], v199 offset:21504
	ds_read_b128 v[186:189], v199 offset:22528
	ds_read_b128 v[194:197], v199 offset:23552
	global_load_lds_dwordx4 v[200:201], off
	s_add_i32 m0, s52, 0x2000
	s_add_u32 s52, s28, 0x40000
	v_lshl_add_u64 v[208:209], s[28:29], 0, v[202:203]
	s_addc_u32 s53, s29, 0
	s_add_i32 s54, s54, s39
	global_load_lds_dwordx4 v[208:209], off
	v_lshl_add_u64 v[210:211], s[52:53], 0, v[96:97]
	s_mov_b32 m0, s54
	v_lshl_add_u64 v[212:213], s[30:31], 0, v[192:193]
	global_load_lds_dwordx4 v[210:211], off
	v_lshl_add_u64 v[210:211], s[52:53], 0, v[202:203]
	s_add_i32 m0, s54, 0x2000
	s_nop 0
	global_load_lds_dwordx4 v[210:211], off
	v_lshl_add_u64 v[210:211], s[30:31], 0, v[190:191]
	s_mov_b32 m0, s40
	s_nop 0
	global_load_lds_dwordx4 v[210:211], off
	s_mov_b32 m0, s41
	s_nop 0
	global_load_lds_dwordx4 v[212:213], off
	s_waitcnt vmcnt(8)
	s_waitcnt lgkmcnt(0)
	s_barrier
	s_setprio 1
	s_waitcnt lgkmcnt(0)
	v_mfma_f32_16x16x32_bf16 v[60:63], v[122:125], v[162:165], 0
	v_mfma_f32_16x16x32_bf16 v[56:59], v[130:133], v[162:165], 0
	v_mfma_f32_16x16x32_bf16 v[44:47], v[122:125], v[170:173], 0
	v_mfma_f32_16x16x32_bf16 v[40:43], v[130:133], v[170:173], 0
	v_mfma_f32_16x16x32_bf16 v[28:31], v[122:125], v[178:181], 0
	v_mfma_f32_16x16x32_bf16 v[24:27], v[130:133], v[178:181], 0
	v_mfma_f32_16x16x32_bf16 v[12:15], v[122:125], v[186:189], 0
	v_mfma_f32_16x16x32_bf16 v[8:11], v[130:133], v[186:189], 0
	v_mfma_f32_16x16x32_bf16 v[60:63], v[126:129], v[166:169], v[60:63]
	v_mfma_f32_16x16x32_bf16 v[56:59], v[134:137], v[166:169], v[56:59]
	v_mfma_f32_16x16x32_bf16 v[44:47], v[126:129], v[174:177], v[44:47]
	v_mfma_f32_16x16x32_bf16 v[40:43], v[134:137], v[174:177], v[40:43]
	v_mfma_f32_16x16x32_bf16 v[28:31], v[126:129], v[182:185], v[28:31]
	v_mfma_f32_16x16x32_bf16 v[24:27], v[134:137], v[182:185], v[24:27]
	v_mfma_f32_16x16x32_bf16 v[12:15], v[126:129], v[194:197], v[12:15]
	v_mfma_f32_16x16x32_bf16 v[8:11], v[134:137], v[194:197], v[8:11]
	s_setprio 0
	s_setprio 1
	v_mfma_f32_16x16x32_bf16 v[52:55], v[138:141], v[162:165], 0
	v_mfma_f32_16x16x32_bf16 v[48:51], v[146:149], v[162:165], 0
	v_mfma_f32_16x16x32_bf16 v[36:39], v[138:141], v[170:173], 0
	v_mfma_f32_16x16x32_bf16 v[32:35], v[146:149], v[170:173], 0
	v_mfma_f32_16x16x32_bf16 v[20:23], v[138:141], v[178:181], 0
	v_mfma_f32_16x16x32_bf16 v[16:19], v[146:149], v[178:181], 0
	v_mfma_f32_16x16x32_bf16 v[4:7], v[138:141], v[186:189], 0
	v_mfma_f32_16x16x32_bf16 v[0:3], v[146:149], v[186:189], 0
	v_mfma_f32_16x16x32_bf16 v[52:55], v[142:145], v[166:169], v[52:55]
	v_mfma_f32_16x16x32_bf16 v[48:51], v[150:153], v[166:169], v[48:51]
	v_mfma_f32_16x16x32_bf16 v[36:39], v[142:145], v[174:177], v[36:39]
	v_mfma_f32_16x16x32_bf16 v[32:35], v[150:153], v[174:177], v[32:35]
	v_mfma_f32_16x16x32_bf16 v[20:23], v[142:145], v[182:185], v[20:23]
	v_mfma_f32_16x16x32_bf16 v[16:19], v[150:153], v[182:185], v[16:19]
	v_mfma_f32_16x16x32_bf16 v[4:7], v[142:145], v[194:197], v[4:7]
	v_mfma_f32_16x16x32_bf16 v[0:3], v[150:153], v[194:197], v[0:3]
	s_setprio 0
	s_barrier
	s_add_i32 s52, 0, 0x18000
	s_add_i32 s53, 0, 0x1c000
	v_add_u32_e32 v134, s52, v245
	v_add_u32_e32 v150, s53, v245
	ds_read_b128 v[122:125], v134
	ds_read_b128 v[126:129], v134 offset:1024
	ds_read_b128 v[130:133], v134 offset:2048
	ds_read_b128 v[134:137], v134 offset:3072
	ds_read_b128 v[138:141], v150
	ds_read_b128 v[142:145], v150 offset:1024
	ds_read_b128 v[146:149], v150 offset:2048
	ds_read_b128 v[150:153], v150 offset:3072
	s_add_u32 s30, s30, 0x40000
	s_addc_u32 s31, s31, 0
	s_mov_b32 m0, s42
	v_lshl_add_u64 v[214:215], s[30:31], 0, v[190:191]
	ds_read_b128 v[162:165], v199 offset:32768
	ds_read_b128 v[166:169], v199 offset:33792
	ds_read_b128 v[170:173], v199 offset:34816
	ds_read_b128 v[174:177], v199 offset:35840
	ds_read_b128 v[178:181], v199 offset:36864
	ds_read_b128 v[182:185], v199 offset:37888
	ds_read_b128 v[186:189], v199 offset:38912
	ds_read_b128 v[194:197], v199 offset:39936
	global_load_lds_dwordx4 v[214:215], off
	v_lshl_add_u64 v[214:215], s[30:31], 0, v[192:193]
	s_mov_b32 m0, s43
	s_nop 0
	global_load_lds_dwordx4 v[214:215], off
	s_waitcnt vmcnt(8)
	s_waitcnt lgkmcnt(0)
	s_barrier
	s_setprio 1
	s_waitcnt lgkmcnt(0)
	v_mfma_f32_16x16x32_bf16 v[158:161], v[122:125], v[162:165], v[158:161]
	v_mfma_f32_16x16x32_bf16 v[154:157], v[130:133], v[162:165], v[154:157]
	v_mfma_f32_16x16x32_bf16 v[110:113], v[122:125], v[170:173], v[110:113]
	v_mfma_f32_16x16x32_bf16 v[106:109], v[130:133], v[170:173], v[106:109]
	v_mfma_f32_16x16x32_bf16 v[92:95], v[122:125], v[178:181], v[92:95]
	v_mfma_f32_16x16x32_bf16 v[88:91], v[130:133], v[178:181], v[88:91]
	v_mfma_f32_16x16x32_bf16 v[76:79], v[122:125], v[186:189], v[76:79]
	v_mfma_f32_16x16x32_bf16 v[72:75], v[130:133], v[186:189], v[72:75]
	v_mfma_f32_16x16x32_bf16 v[158:161], v[126:129], v[166:169], v[158:161]
	v_mfma_f32_16x16x32_bf16 v[154:157], v[134:137], v[166:169], v[154:157]
	v_mfma_f32_16x16x32_bf16 v[110:113], v[126:129], v[174:177], v[110:113]
	v_mfma_f32_16x16x32_bf16 v[106:109], v[134:137], v[174:177], v[106:109]
	v_mfma_f32_16x16x32_bf16 v[92:95], v[126:129], v[182:185], v[92:95]
	v_mfma_f32_16x16x32_bf16 v[88:91], v[134:137], v[182:185], v[88:91]
	v_mfma_f32_16x16x32_bf16 v[76:79], v[126:129], v[194:197], v[76:79]
	v_mfma_f32_16x16x32_bf16 v[72:75], v[134:137], v[194:197], v[72:75]
	s_setprio 0
	s_setprio 1
	v_mfma_f32_16x16x32_bf16 v[118:121], v[138:141], v[162:165], v[118:121]
	v_mfma_f32_16x16x32_bf16 v[114:117], v[146:149], v[162:165], v[114:117]
	v_mfma_f32_16x16x32_bf16 v[102:105], v[138:141], v[170:173], v[102:105]
	v_mfma_f32_16x16x32_bf16 v[98:101], v[146:149], v[170:173], v[98:101]
	v_mfma_f32_16x16x32_bf16 v[84:87], v[138:141], v[178:181], v[84:87]
	v_mfma_f32_16x16x32_bf16 v[80:83], v[146:149], v[178:181], v[80:83]
	v_mfma_f32_16x16x32_bf16 v[68:71], v[138:141], v[186:189], v[68:71]
	v_mfma_f32_16x16x32_bf16 v[64:67], v[146:149], v[186:189], v[64:67]
	v_mfma_f32_16x16x32_bf16 v[118:121], v[142:145], v[166:169], v[118:121]
	v_mfma_f32_16x16x32_bf16 v[114:117], v[150:153], v[166:169], v[114:117]
	v_mfma_f32_16x16x32_bf16 v[102:105], v[142:145], v[174:177], v[102:105]
	v_mfma_f32_16x16x32_bf16 v[98:101], v[150:153], v[174:177], v[98:101]
	v_mfma_f32_16x16x32_bf16 v[84:87], v[142:145], v[182:185], v[84:87]
	v_mfma_f32_16x16x32_bf16 v[80:83], v[150:153], v[182:185], v[80:83]
	v_mfma_f32_16x16x32_bf16 v[68:71], v[142:145], v[194:197], v[68:71]
	v_mfma_f32_16x16x32_bf16 v[64:67], v[150:153], v[194:197], v[64:67]
	s_setprio 0
	s_barrier
	s_add_i32 s30, s52, s39
	v_lshl_add_u64 v[200:201], v[200:201], 0, s[64:65]
	s_mov_b32 m0, s30
	ds_read_b128 v[162:165], v199 offset:49152
	ds_read_b128 v[166:169], v199 offset:50176
	ds_read_b128 v[170:173], v199 offset:51200
	ds_read_b128 v[174:177], v199 offset:52224
	ds_read_b128 v[178:181], v199 offset:53248
	ds_read_b128 v[182:185], v199 offset:54272
	ds_read_b128 v[186:189], v199 offset:55296
	ds_read_b128 v[194:197], v199 offset:56320
	global_load_lds_dwordx4 v[200:201], off
	s_add_i32 m0, s30, 0x2000
	s_add_u32 s28, s28, 0x40080
	v_lshl_add_u64 v[200:201], v[208:209], 0, s[64:65]
	s_addc_u32 s29, s29, 0
	s_add_i32 s30, s53, s39
	global_load_lds_dwordx4 v[200:201], off
	v_lshl_add_u64 v[200:201], s[28:29], 0, v[96:97]
	s_mov_b32 m0, s30
	s_nop 0
	global_load_lds_dwordx4 v[200:201], off
	v_lshl_add_u64 v[200:201], s[28:29], 0, v[202:203]
	s_add_i32 m0, s30, 0x2000
	s_nop 0
	global_load_lds_dwordx4 v[200:201], off
	v_lshl_add_u64 v[200:201], v[210:211], 0, s[64:65]
	s_mov_b32 m0, s45
	s_nop 0
	global_load_lds_dwordx4 v[200:201], off
	v_lshl_add_u64 v[200:201], v[212:213], 0, s[64:65]
	s_mov_b32 m0, s46
	s_nop 0
	global_load_lds_dwordx4 v[200:201], off
	s_waitcnt vmcnt(8)
	s_waitcnt lgkmcnt(0)
	s_barrier
	s_setprio 1
	s_waitcnt lgkmcnt(0)
	v_mfma_f32_16x16x32_bf16 v[60:63], v[122:125], v[162:165], v[60:63]
	v_mfma_f32_16x16x32_bf16 v[56:59], v[130:133], v[162:165], v[56:59]
	v_mfma_f32_16x16x32_bf16 v[44:47], v[122:125], v[170:173], v[44:47]
	v_mfma_f32_16x16x32_bf16 v[40:43], v[130:133], v[170:173], v[40:43]
	v_mfma_f32_16x16x32_bf16 v[28:31], v[122:125], v[178:181], v[28:31]
	v_mfma_f32_16x16x32_bf16 v[24:27], v[130:133], v[178:181], v[24:27]
	v_mfma_f32_16x16x32_bf16 v[12:15], v[122:125], v[186:189], v[12:15]
	v_mfma_f32_16x16x32_bf16 v[8:11], v[130:133], v[186:189], v[8:11]
	v_mfma_f32_16x16x32_bf16 v[60:63], v[126:129], v[166:169], v[60:63]
	v_mfma_f32_16x16x32_bf16 v[56:59], v[134:137], v[166:169], v[56:59]
	v_mfma_f32_16x16x32_bf16 v[44:47], v[126:129], v[174:177], v[44:47]
	v_mfma_f32_16x16x32_bf16 v[40:43], v[134:137], v[174:177], v[40:43]
	v_mfma_f32_16x16x32_bf16 v[28:31], v[126:129], v[182:185], v[28:31]
	v_mfma_f32_16x16x32_bf16 v[24:27], v[134:137], v[182:185], v[24:27]
	v_mfma_f32_16x16x32_bf16 v[12:15], v[126:129], v[194:197], v[12:15]
	v_mfma_f32_16x16x32_bf16 v[8:11], v[134:137], v[194:197], v[8:11]
	s_setprio 0
	s_setprio 1
	v_mfma_f32_16x16x32_bf16 v[52:55], v[138:141], v[162:165], v[52:55]
	v_mfma_f32_16x16x32_bf16 v[48:51], v[146:149], v[162:165], v[48:51]
	v_mfma_f32_16x16x32_bf16 v[36:39], v[138:141], v[170:173], v[36:39]
	v_mfma_f32_16x16x32_bf16 v[32:35], v[146:149], v[170:173], v[32:35]
	v_mfma_f32_16x16x32_bf16 v[20:23], v[138:141], v[178:181], v[20:23]
	v_mfma_f32_16x16x32_bf16 v[16:19], v[146:149], v[178:181], v[16:19]
	v_mfma_f32_16x16x32_bf16 v[4:7], v[138:141], v[186:189], v[4:7]
	v_mfma_f32_16x16x32_bf16 v[0:3], v[146:149], v[186:189], v[0:3]
	v_mfma_f32_16x16x32_bf16 v[52:55], v[142:145], v[166:169], v[52:55]
	v_mfma_f32_16x16x32_bf16 v[48:51], v[150:153], v[166:169], v[48:51]
	v_mfma_f32_16x16x32_bf16 v[36:39], v[142:145], v[174:177], v[36:39]
	v_mfma_f32_16x16x32_bf16 v[32:35], v[150:153], v[174:177], v[32:35]
	v_mfma_f32_16x16x32_bf16 v[20:23], v[142:145], v[182:185], v[20:23]
	v_mfma_f32_16x16x32_bf16 v[16:19], v[150:153], v[182:185], v[16:19]
	v_mfma_f32_16x16x32_bf16 v[4:7], v[142:145], v[194:197], v[4:7]
	v_mfma_f32_16x16x32_bf16 v[0:3], v[150:153], v[194:197], v[0:3]
	s_setprio 0
	s_barrier
	s_add_i32 s51, s51, 2
	s_add_u32 s26, s26, 0x100
	s_addc_u32 s27, s27, 0
	s_add_u32 s49, s49, 0x100
	s_addc_u32 s50, s50, 0
	s_cmp_gt_u32 s51, 13
	s_cbranch_scc1 .Lpeel_done_634

.Lpeel_done_634:
	s_and_b64 vcc, exec, s[12:13]
	s_cbranch_vccz .LBB0_637
	s_barrier

.LBB0_721:
	s_ashr_i32 s17, s16, 31
	s_lshl_b64 s[18:19], s[16:17], 19
	s_add_u32 s18, s35, s18
	s_addc_u32 s19, s36, s19
	s_and_b64 s[20:21], s[2:3], exec
	s_cselect_b32 s17, s19, s25
	s_cselect_b32 s48, s18, s24
	s_ashr_i32 s15, s14, 31
	s_lshl_b64 s[20:21], s[14:15], 19
	s_add_u32 s20, s31, s20
	s_addc_u32 s21, s34, s21
	s_and_b64 s[28:29], s[2:3], exec
	s_cselect_b32 s15, s21, s27
	s_cselect_b32 s49, s20, s26
	s_add_u32 s24, s24, 0x40080
	s_addc_u32 s25, s25, 0
	s_add_u32 s50, s26, 0x100
	s_addc_u32 s51, s27, 0
	s_mov_b32 s52, -2
	s_add_u32 s26, s24, 0xfffc0080
	s_addc_u32 s27, s25, -1
	s_add_i32 s53, 0, 0x10000
	s_cmp_eq_u32 s52, 12
	s_cselect_b32 s29, s17, s27
	s_cselect_b32 s28, s48, s26
	v_add_u32_e32 v147, s53, v141
	s_cselect_b32 s27, s15, s51
	s_cselect_b32 s26, s49, s50
	s_add_i32 s56, 0, 0x14000
	ds_read_b128 v[148:151], v147
	ds_read_b128 v[152:155], v147 offset:1024
	ds_read_b128 v[156:159], v147 offset:2048
	ds_read_b128 v[160:163], v147 offset:3072
	v_add_u32_e32 v147, s56, v141
	ds_read_b128 v[164:167], v147
	ds_read_b128 v[168:171], v147 offset:1024
	ds_read_b128 v[172:175], v147 offset:2048
	ds_read_b128 v[176:179], v147 offset:3072
	v_lshl_add_u64 v[192:193], s[24:25], 0, v[136:137]
	s_add_i32 m0, s23, 0xc000
	ds_read_b128 v[180:183], v146
	ds_read_b128 v[184:187], v146 offset:1024
	ds_read_b128 v[188:191], v146 offset:2048
	ds_read_b128 v[202:205], v146 offset:3072
	ds_read_b128 v[206:209], v146 offset:4096
	ds_read_b128 v[210:213], v146 offset:5120
	ds_read_b128 v[214:217], v146 offset:6144
	ds_read_b128 v[218:221], v146 offset:7168
	global_load_lds_dwordx4 v[192:193], off
	v_lshl_add_u64 v[192:193], s[24:25], 0, v[138:139]
	s_add_i32 m0, s23, 0xe000
	s_nop 0
	global_load_lds_dwordx4 v[192:193], off
	s_waitcnt vmcnt(8)
	s_waitcnt lgkmcnt(0)
	s_barrier
	s_setprio 1
	s_waitcnt lgkmcnt(0)
	v_mfma_f32_16x16x32_bf16 v[126:129], v[148:151], v[180:183], 0
	v_mfma_f32_16x16x32_bf16 v[122:125], v[156:159], v[180:183], 0
	v_mfma_f32_16x16x32_bf16 v[114:117], v[148:151], v[188:191], 0
	v_mfma_f32_16x16x32_bf16 v[106:109], v[156:159], v[188:191], 0
	v_mfma_f32_16x16x32_bf16 v[98:101], v[148:151], v[206:209], 0
	v_mfma_f32_16x16x32_bf16 v[88:91], v[156:159], v[206:209], 0
	v_mfma_f32_16x16x32_bf16 v[80:83], v[148:151], v[214:217], 0
	v_mfma_f32_16x16x32_bf16 v[72:75], v[156:159], v[214:217], 0
	v_mfma_f32_16x16x32_bf16 v[126:129], v[152:155], v[184:187], v[126:129]
	v_mfma_f32_16x16x32_bf16 v[122:125], v[160:163], v[184:187], v[122:125]
	v_mfma_f32_16x16x32_bf16 v[114:117], v[152:155], v[202:205], v[114:117]
	v_mfma_f32_16x16x32_bf16 v[106:109], v[160:163], v[202:205], v[106:109]
	v_mfma_f32_16x16x32_bf16 v[98:101], v[152:155], v[210:213], v[98:101]
	v_mfma_f32_16x16x32_bf16 v[88:91], v[160:163], v[210:213], v[88:91]
	v_mfma_f32_16x16x32_bf16 v[80:83], v[152:155], v[218:221], v[80:83]
	v_mfma_f32_16x16x32_bf16 v[72:75], v[160:163], v[218:221], v[72:75]
	s_setprio 0
	s_setprio 1
	v_mfma_f32_16x16x32_bf16 v[118:121], v[164:167], v[180:183], 0
	v_mfma_f32_16x16x32_bf16 v[110:113], v[172:175], v[180:183], 0
	v_mfma_f32_16x16x32_bf16 v[102:105], v[164:167], v[188:191], 0
	v_mfma_f32_16x16x32_bf16 v[92:95], v[172:175], v[188:191], 0
	v_mfma_f32_16x16x32_bf16 v[84:87], v[164:167], v[206:209], 0
	v_mfma_f32_16x16x32_bf16 v[76:79], v[172:175], v[206:209], 0
	v_mfma_f32_16x16x32_bf16 v[68:71], v[164:167], v[214:217], 0
	v_mfma_f32_16x16x32_bf16 v[64:67], v[172:175], v[214:217], 0
	v_mfma_f32_16x16x32_bf16 v[118:121], v[168:171], v[184:187], v[118:121]
	v_mfma_f32_16x16x32_bf16 v[110:113], v[176:179], v[184:187], v[110:113]
	v_mfma_f32_16x16x32_bf16 v[102:105], v[168:171], v[202:205], v[102:105]
	v_mfma_f32_16x16x32_bf16 v[92:95], v[176:179], v[202:205], v[92:95]
	v_mfma_f32_16x16x32_bf16 v[84:87], v[168:171], v[210:213], v[84:87]
	v_mfma_f32_16x16x32_bf16 v[76:79], v[176:179], v[210:213], v[76:79]
	v_mfma_f32_16x16x32_bf16 v[68:71], v[168:171], v[218:221], v[68:71]
	v_mfma_f32_16x16x32_bf16 v[64:67], v[176:179], v[218:221], v[64:67]
	s_setprio 0
	s_barrier
	s_add_i32 s53, s53, s38
	v_lshl_add_u64 v[192:193], s[26:27], 0, v[96:97]
	s_mov_b32 m0, s53
	ds_read_b128 v[180:183], v146 offset:16384
	ds_read_b128 v[184:187], v146 offset:17408
	ds_read_b128 v[188:191], v146 offset:18432
	ds_read_b128 v[202:205], v146 offset:19456
	ds_read_b128 v[206:209], v146 offset:20480
	ds_read_b128 v[210:213], v146 offset:21504
	ds_read_b128 v[214:217], v146 offset:22528
	ds_read_b128 v[218:221], v146 offset:23552
	global_load_lds_dwordx4 v[192:193], off
	s_add_i32 m0, s53, 0x2000
	s_add_u32 s54, s26, 0x40000
	v_lshl_add_u64 v[194:195], s[26:27], 0, v[130:131]
	s_addc_u32 s55, s27, 0
	s_add_i32 s53, s56, s38
	global_load_lds_dwordx4 v[194:195], off
	v_lshl_add_u64 v[196:197], s[54:55], 0, v[96:97]
	s_mov_b32 m0, s53
	v_lshl_add_u64 v[198:199], s[28:29], 0, v[132:133]
	global_load_lds_dwordx4 v[196:197], off
	v_lshl_add_u64 v[196:197], s[54:55], 0, v[130:131]
	s_add_i32 m0, s53, 0x2000
	s_nop 0
	global_load_lds_dwordx4 v[196:197], off
	v_lshl_add_u64 v[196:197], s[28:29], 0, v[134:135]
	s_mov_b32 m0, s23
	s_nop 0
	global_load_lds_dwordx4 v[196:197], off
	s_mov_b32 m0, s39
	s_nop 0
	global_load_lds_dwordx4 v[198:199], off
	s_waitcnt vmcnt(8)
	s_waitcnt lgkmcnt(0)
	s_barrier
	s_setprio 1
	s_waitcnt lgkmcnt(0)
	v_mfma_f32_16x16x32_bf16 v[60:63], v[148:151], v[180:183], 0
	v_mfma_f32_16x16x32_bf16 v[56:59], v[156:159], v[180:183], 0
	v_mfma_f32_16x16x32_bf16 v[48:51], v[148:151], v[188:191], 0
	v_mfma_f32_16x16x32_bf16 v[40:43], v[156:159], v[188:191], 0
	v_mfma_f32_16x16x32_bf16 v[32:35], v[148:151], v[206:209], 0
	v_mfma_f32_16x16x32_bf16 v[24:27], v[156:159], v[206:209], 0
	v_mfma_f32_16x16x32_bf16 v[16:19], v[148:151], v[214:217], 0
	v_mfma_f32_16x16x32_bf16 v[8:11], v[156:159], v[214:217], 0
	v_mfma_f32_16x16x32_bf16 v[60:63], v[152:155], v[184:187], v[60:63]
	v_mfma_f32_16x16x32_bf16 v[56:59], v[160:163], v[184:187], v[56:59]
	v_mfma_f32_16x16x32_bf16 v[48:51], v[152:155], v[202:205], v[48:51]
	v_mfma_f32_16x16x32_bf16 v[40:43], v[160:163], v[202:205], v[40:43]
	v_mfma_f32_16x16x32_bf16 v[32:35], v[152:155], v[210:213], v[32:35]
	v_mfma_f32_16x16x32_bf16 v[24:27], v[160:163], v[210:213], v[24:27]
	v_mfma_f32_16x16x32_bf16 v[16:19], v[152:155], v[218:221], v[16:19]
	v_mfma_f32_16x16x32_bf16 v[8:11], v[160:163], v[218:221], v[8:11]
	s_setprio 0
	s_setprio 1
	v_mfma_f32_16x16x32_bf16 v[52:55], v[164:167], v[180:183], 0
	v_mfma_f32_16x16x32_bf16 v[44:47], v[172:175], v[180:183], 0
	v_mfma_f32_16x16x32_bf16 v[36:39], v[164:167], v[188:191], 0
	v_mfma_f32_16x16x32_bf16 v[28:31], v[172:175], v[188:191], 0
	v_mfma_f32_16x16x32_bf16 v[20:23], v[164:167], v[206:209], 0
	v_mfma_f32_16x16x32_bf16 v[12:15], v[172:175], v[206:209], 0
	v_mfma_f32_16x16x32_bf16 v[4:7], v[164:167], v[214:217], 0
	v_mfma_f32_16x16x32_bf16 v[0:3], v[172:175], v[214:217], 0
	v_mfma_f32_16x16x32_bf16 v[52:55], v[168:171], v[184:187], v[52:55]
	v_mfma_f32_16x16x32_bf16 v[44:47], v[176:179], v[184:187], v[44:47]
	v_mfma_f32_16x16x32_bf16 v[36:39], v[168:171], v[202:205], v[36:39]
	v_mfma_f32_16x16x32_bf16 v[28:31], v[176:179], v[202:205], v[28:31]
	v_mfma_f32_16x16x32_bf16 v[20:23], v[168:171], v[210:213], v[20:23]
	v_mfma_f32_16x16x32_bf16 v[12:15], v[176:179], v[210:213], v[12:15]
	v_mfma_f32_16x16x32_bf16 v[4:7], v[168:171], v[218:221], v[4:7]
	v_mfma_f32_16x16x32_bf16 v[0:3], v[176:179], v[218:221], v[0:3]
	s_setprio 0
	s_barrier
	s_add_i32 s53, 0, 0x18000
	v_add_u32_e32 v147, s53, v141
	s_add_i32 s54, 0, 0x1c000
	ds_read_b128 v[148:151], v147
	ds_read_b128 v[152:155], v147 offset:1024
	ds_read_b128 v[156:159], v147 offset:2048
	ds_read_b128 v[160:163], v147 offset:3072
	v_add_u32_e32 v147, s54, v141
	ds_read_b128 v[164:167], v147
	ds_read_b128 v[168:171], v147 offset:1024
	ds_read_b128 v[172:175], v147 offset:2048
	ds_read_b128 v[176:179], v147 offset:3072
	s_add_u32 s28, s28, 0x40000
	s_addc_u32 s29, s29, 0
	s_mov_b32 m0, s40
	v_lshl_add_u64 v[200:201], s[28:29], 0, v[134:135]
	ds_read_b128 v[180:183], v146 offset:32768
	ds_read_b128 v[184:187], v146 offset:33792
	ds_read_b128 v[188:191], v146 offset:34816
	ds_read_b128 v[202:205], v146 offset:35840
	ds_read_b128 v[206:209], v146 offset:36864
	ds_read_b128 v[210:213], v146 offset:37888
	ds_read_b128 v[214:217], v146 offset:38912
	ds_read_b128 v[218:221], v146 offset:39936
	global_load_lds_dwordx4 v[200:201], off
	v_lshl_add_u64 v[200:201], s[28:29], 0, v[132:133]
	s_mov_b32 m0, s41
	s_nop 0
	global_load_lds_dwordx4 v[200:201], off
	s_waitcnt vmcnt(8)
	s_waitcnt lgkmcnt(0)
	s_barrier
	s_setprio 1
	s_waitcnt lgkmcnt(0)
	v_mfma_f32_16x16x32_bf16 v[126:129], v[148:151], v[180:183], v[126:129]
	v_mfma_f32_16x16x32_bf16 v[122:125], v[156:159], v[180:183], v[122:125]
	v_mfma_f32_16x16x32_bf16 v[114:117], v[148:151], v[188:191], v[114:117]
	v_mfma_f32_16x16x32_bf16 v[106:109], v[156:159], v[188:191], v[106:109]
	v_mfma_f32_16x16x32_bf16 v[98:101], v[148:151], v[206:209], v[98:101]
	v_mfma_f32_16x16x32_bf16 v[88:91], v[156:159], v[206:209], v[88:91]
	v_mfma_f32_16x16x32_bf16 v[80:83], v[148:151], v[214:217], v[80:83]
	v_mfma_f32_16x16x32_bf16 v[72:75], v[156:159], v[214:217], v[72:75]
	v_mfma_f32_16x16x32_bf16 v[126:129], v[152:155], v[184:187], v[126:129]
	v_mfma_f32_16x16x32_bf16 v[122:125], v[160:163], v[184:187], v[122:125]
	v_mfma_f32_16x16x32_bf16 v[114:117], v[152:155], v[202:205], v[114:117]
	v_mfma_f32_16x16x32_bf16 v[106:109], v[160:163], v[202:205], v[106:109]
	v_mfma_f32_16x16x32_bf16 v[98:101], v[152:155], v[210:213], v[98:101]
	v_mfma_f32_16x16x32_bf16 v[88:91], v[160:163], v[210:213], v[88:91]
	v_mfma_f32_16x16x32_bf16 v[80:83], v[152:155], v[218:221], v[80:83]
	v_mfma_f32_16x16x32_bf16 v[72:75], v[160:163], v[218:221], v[72:75]
	s_setprio 0
	s_setprio 1
	v_mfma_f32_16x16x32_bf16 v[118:121], v[164:167], v[180:183], v[118:121]
	v_mfma_f32_16x16x32_bf16 v[110:113], v[172:175], v[180:183], v[110:113]
	v_mfma_f32_16x16x32_bf16 v[102:105], v[164:167], v[188:191], v[102:105]
	v_mfma_f32_16x16x32_bf16 v[92:95], v[172:175], v[188:191], v[92:95]
	v_mfma_f32_16x16x32_bf16 v[84:87], v[164:167], v[206:209], v[84:87]
	v_mfma_f32_16x16x32_bf16 v[76:79], v[172:175], v[206:209], v[76:79]
	v_mfma_f32_16x16x32_bf16 v[68:71], v[164:167], v[214:217], v[68:71]
	v_mfma_f32_16x16x32_bf16 v[64:67], v[172:175], v[214:217], v[64:67]
	v_mfma_f32_16x16x32_bf16 v[118:121], v[168:171], v[184:187], v[118:121]
	v_mfma_f32_16x16x32_bf16 v[110:113], v[176:179], v[184:187], v[110:113]
	v_mfma_f32_16x16x32_bf16 v[102:105], v[168:171], v[202:205], v[102:105]
	v_mfma_f32_16x16x32_bf16 v[92:95], v[176:179], v[202:205], v[92:95]
	v_mfma_f32_16x16x32_bf16 v[84:87], v[168:171], v[210:213], v[84:87]
	v_mfma_f32_16x16x32_bf16 v[76:79], v[176:179], v[210:213], v[76:79]
	v_mfma_f32_16x16x32_bf16 v[68:71], v[168:171], v[218:221], v[68:71]
	v_mfma_f32_16x16x32_bf16 v[64:67], v[176:179], v[218:221], v[64:67]
	s_setprio 0
	s_barrier
	s_add_i32 s28, s53, s38
	v_lshl_add_u64 v[192:193], v[192:193], 0, s[64:65]
	s_mov_b32 m0, s28
	ds_read_b128 v[180:183], v146 offset:49152
	ds_read_b128 v[184:187], v146 offset:50176
	ds_read_b128 v[188:191], v146 offset:51200
	ds_read_b128 v[202:205], v146 offset:52224
	ds_read_b128 v[206:209], v146 offset:53248
	ds_read_b128 v[210:213], v146 offset:54272
	ds_read_b128 v[214:217], v146 offset:55296
	ds_read_b128 v[218:221], v146 offset:56320
	global_load_lds_dwordx4 v[192:193], off
	s_add_i32 m0, s28, 0x2000
	s_add_u32 s26, s26, 0x40080
	v_lshl_add_u64 v[192:193], v[194:195], 0, s[64:65]
	s_addc_u32 s27, s27, 0
	s_add_i32 s28, s54, s38
	global_load_lds_dwordx4 v[192:193], off
	v_lshl_add_u64 v[192:193], s[26:27], 0, v[96:97]
	s_mov_b32 m0, s28
	s_nop 0
	global_load_lds_dwordx4 v[192:193], off
	v_lshl_add_u64 v[192:193], s[26:27], 0, v[130:131]
	s_add_i32 m0, s28, 0x2000
	s_nop 0
	global_load_lds_dwordx4 v[192:193], off
	v_lshl_add_u64 v[192:193], v[196:197], 0, s[64:65]
	s_mov_b32 m0, s42
	s_nop 0
	global_load_lds_dwordx4 v[192:193], off
	v_lshl_add_u64 v[192:193], v[198:199], 0, s[64:65]
	s_mov_b32 m0, s43
	s_nop 0
	global_load_lds_dwordx4 v[192:193], off
	s_waitcnt vmcnt(8)
	s_waitcnt lgkmcnt(0)
	s_barrier
	s_setprio 1
	s_waitcnt lgkmcnt(0)
	v_mfma_f32_16x16x32_bf16 v[60:63], v[148:151], v[180:183], v[60:63]
	v_mfma_f32_16x16x32_bf16 v[56:59], v[156:159], v[180:183], v[56:59]
	v_mfma_f32_16x16x32_bf16 v[48:51], v[148:151], v[188:191], v[48:51]
	v_mfma_f32_16x16x32_bf16 v[40:43], v[156:159], v[188:191], v[40:43]
	v_mfma_f32_16x16x32_bf16 v[32:35], v[148:151], v[206:209], v[32:35]
	v_mfma_f32_16x16x32_bf16 v[24:27], v[156:159], v[206:209], v[24:27]
	v_mfma_f32_16x16x32_bf16 v[16:19], v[148:151], v[214:217], v[16:19]
	v_mfma_f32_16x16x32_bf16 v[8:11], v[156:159], v[214:217], v[8:11]
	v_mfma_f32_16x16x32_bf16 v[60:63], v[152:155], v[184:187], v[60:63]
	v_mfma_f32_16x16x32_bf16 v[56:59], v[160:163], v[184:187], v[56:59]
	v_mfma_f32_16x16x32_bf16 v[48:51], v[152:155], v[202:205], v[48:51]
	v_mfma_f32_16x16x32_bf16 v[40:43], v[160:163], v[202:205], v[40:43]
	v_mfma_f32_16x16x32_bf16 v[32:35], v[152:155], v[210:213], v[32:35]
	v_mfma_f32_16x16x32_bf16 v[24:27], v[160:163], v[210:213], v[24:27]
	v_mfma_f32_16x16x32_bf16 v[16:19], v[152:155], v[218:221], v[16:19]
	v_mfma_f32_16x16x32_bf16 v[8:11], v[160:163], v[218:221], v[8:11]
	s_setprio 0
	s_setprio 1
	v_mfma_f32_16x16x32_bf16 v[52:55], v[164:167], v[180:183], v[52:55]
	v_mfma_f32_16x16x32_bf16 v[44:47], v[172:175], v[180:183], v[44:47]
	v_mfma_f32_16x16x32_bf16 v[36:39], v[164:167], v[188:191], v[36:39]
	v_mfma_f32_16x16x32_bf16 v[28:31], v[172:175], v[188:191], v[28:31]
	v_mfma_f32_16x16x32_bf16 v[20:23], v[164:167], v[206:209], v[20:23]
	v_mfma_f32_16x16x32_bf16 v[12:15], v[172:175], v[206:209], v[12:15]
	v_mfma_f32_16x16x32_bf16 v[4:7], v[164:167], v[214:217], v[4:7]
	v_mfma_f32_16x16x32_bf16 v[0:3], v[172:175], v[214:217], v[0:3]
	v_mfma_f32_16x16x32_bf16 v[52:55], v[168:171], v[184:187], v[52:55]
	v_mfma_f32_16x16x32_bf16 v[44:47], v[176:179], v[184:187], v[44:47]
	v_mfma_f32_16x16x32_bf16 v[36:39], v[168:171], v[202:205], v[36:39]
	v_mfma_f32_16x16x32_bf16 v[28:31], v[176:179], v[202:205], v[28:31]
	v_mfma_f32_16x16x32_bf16 v[20:23], v[168:171], v[210:213], v[20:23]
	v_mfma_f32_16x16x32_bf16 v[12:15], v[176:179], v[210:213], v[12:15]
	v_mfma_f32_16x16x32_bf16 v[4:7], v[168:171], v[218:221], v[4:7]
	v_mfma_f32_16x16x32_bf16 v[0:3], v[176:179], v[218:221], v[0:3]
	s_setprio 0
	s_barrier
	s_add_i32 s52, s52, 2
	s_add_u32 s24, s24, 0x100
	s_addc_u32 s25, s25, 0
	s_add_u32 s50, s50, 0x100
	s_addc_u32 s51, s51, 0
	s_cmp_gt_u32 s52, 13
	s_cbranch_scc1 .Lpeel_done_722
.LBB0_722:
	s_add_u32 s26, s24, 0xfffc0080
	s_addc_u32 s27, s25, -1
	s_add_i32 s53, 0, 0x10000
	s_cmp_eq_u32 s52, 12
	s_cselect_b32 s29, s17, s27
	s_cselect_b32 s28, s48, s26
	v_add_u32_e32 v147, s53, v141
	s_cselect_b32 s27, s15, s51
	s_cselect_b32 s26, s49, s50
	s_add_i32 s56, 0, 0x14000
	ds_read_b128 v[148:151], v147
	ds_read_b128 v[152:155], v147 offset:1024
	ds_read_b128 v[156:159], v147 offset:2048
	ds_read_b128 v[160:163], v147 offset:3072
	v_add_u32_e32 v147, s56, v141
	ds_read_b128 v[164:167], v147
	ds_read_b128 v[168:171], v147 offset:1024
	ds_read_b128 v[172:175], v147 offset:2048
	ds_read_b128 v[176:179], v147 offset:3072
	v_lshl_add_u64 v[192:193], s[24:25], 0, v[136:137]
	s_add_i32 m0, s23, 0xc000
	ds_read_b128 v[180:183], v146
	ds_read_b128 v[184:187], v146 offset:1024
	ds_read_b128 v[188:191], v146 offset:2048
	ds_read_b128 v[202:205], v146 offset:3072
	ds_read_b128 v[206:209], v146 offset:4096
	ds_read_b128 v[210:213], v146 offset:5120
	ds_read_b128 v[214:217], v146 offset:6144
	ds_read_b128 v[218:221], v146 offset:7168
	global_load_lds_dwordx4 v[192:193], off
	v_lshl_add_u64 v[192:193], s[24:25], 0, v[138:139]
	s_add_i32 m0, s23, 0xe000
	s_nop 0
	global_load_lds_dwordx4 v[192:193], off
	s_waitcnt vmcnt(8)
	s_waitcnt lgkmcnt(0)
	s_barrier
	s_setprio 1
	s_waitcnt lgkmcnt(0)
	v_mfma_f32_16x16x32_bf16 v[126:129], v[148:151], v[180:183], v[126:129]
	v_mfma_f32_16x16x32_bf16 v[122:125], v[156:159], v[180:183], v[122:125]
	v_mfma_f32_16x16x32_bf16 v[114:117], v[148:151], v[188:191], v[114:117]
	v_mfma_f32_16x16x32_bf16 v[106:109], v[156:159], v[188:191], v[106:109]
	v_mfma_f32_16x16x32_bf16 v[98:101], v[148:151], v[206:209], v[98:101]
	v_mfma_f32_16x16x32_bf16 v[88:91], v[156:159], v[206:209], v[88:91]
	v_mfma_f32_16x16x32_bf16 v[80:83], v[148:151], v[214:217], v[80:83]
	v_mfma_f32_16x16x32_bf16 v[72:75], v[156:159], v[214:217], v[72:75]
	v_mfma_f32_16x16x32_bf16 v[126:129], v[152:155], v[184:187], v[126:129]
	v_mfma_f32_16x16x32_bf16 v[122:125], v[160:163], v[184:187], v[122:125]
	v_mfma_f32_16x16x32_bf16 v[114:117], v[152:155], v[202:205], v[114:117]
	v_mfma_f32_16x16x32_bf16 v[106:109], v[160:163], v[202:205], v[106:109]
	v_mfma_f32_16x16x32_bf16 v[98:101], v[152:155], v[210:213], v[98:101]
	v_mfma_f32_16x16x32_bf16 v[88:91], v[160:163], v[210:213], v[88:91]
	v_mfma_f32_16x16x32_bf16 v[80:83], v[152:155], v[218:221], v[80:83]
	v_mfma_f32_16x16x32_bf16 v[72:75], v[160:163], v[218:221], v[72:75]
	s_setprio 0
	s_setprio 1
	v_mfma_f32_16x16x32_bf16 v[118:121], v[164:167], v[180:183], v[118:121]
	v_mfma_f32_16x16x32_bf16 v[110:113], v[172:175], v[180:183], v[110:113]
	v_mfma_f32_16x16x32_bf16 v[102:105], v[164:167], v[188:191], v[102:105]
	v_mfma_f32_16x16x32_bf16 v[92:95], v[172:175], v[188:191], v[92:95]
	v_mfma_f32_16x16x32_bf16 v[84:87], v[164:167], v[206:209], v[84:87]
	v_mfma_f32_16x16x32_bf16 v[76:79], v[172:175], v[206:209], v[76:79]
	v_mfma_f32_16x16x32_bf16 v[68:71], v[164:167], v[214:217], v[68:71]
	v_mfma_f32_16x16x32_bf16 v[64:67], v[172:175], v[214:217], v[64:67]
	v_mfma_f32_16x16x32_bf16 v[118:121], v[168:171], v[184:187], v[118:121]
	v_mfma_f32_16x16x32_bf16 v[110:113], v[176:179], v[184:187], v[110:113]
	v_mfma_f32_16x16x32_bf16 v[102:105], v[168:171], v[202:205], v[102:105]
	v_mfma_f32_16x16x32_bf16 v[92:95], v[176:179], v[202:205], v[92:95]
	v_mfma_f32_16x16x32_bf16 v[84:87], v[168:171], v[210:213], v[84:87]
	v_mfma_f32_16x16x32_bf16 v[76:79], v[176:179], v[210:213], v[76:79]
	v_mfma_f32_16x16x32_bf16 v[68:71], v[168:171], v[218:221], v[68:71]
	v_mfma_f32_16x16x32_bf16 v[64:67], v[176:179], v[218:221], v[64:67]
	s_setprio 0
	s_barrier
	s_add_i32 s53, s53, s38
	v_lshl_add_u64 v[192:193], s[26:27], 0, v[96:97]
	s_mov_b32 m0, s53
	ds_read_b128 v[180:183], v146 offset:16384
	ds_read_b128 v[184:187], v146 offset:17408
	ds_read_b128 v[188:191], v146 offset:18432
	ds_read_b128 v[202:205], v146 offset:19456
	ds_read_b128 v[206:209], v146 offset:20480
	ds_read_b128 v[210:213], v146 offset:21504
	ds_read_b128 v[214:217], v146 offset:22528
	ds_read_b128 v[218:221], v146 offset:23552
	global_load_lds_dwordx4 v[192:193], off
	s_add_i32 m0, s53, 0x2000
	s_add_u32 s54, s26, 0x40000
	v_lshl_add_u64 v[194:195], s[26:27], 0, v[130:131]
	s_addc_u32 s55, s27, 0
	s_add_i32 s53, s56, s38
	global_load_lds_dwordx4 v[194:195], off
	v_lshl_add_u64 v[196:197], s[54:55], 0, v[96:97]
	s_mov_b32 m0, s53
	v_lshl_add_u64 v[198:199], s[28:29], 0, v[132:133]
	global_load_lds_dwordx4 v[196:197], off
	v_lshl_add_u64 v[196:197], s[54:55], 0, v[130:131]
	s_add_i32 m0, s53, 0x2000
	s_nop 0
	global_load_lds_dwordx4 v[196:197], off
	v_lshl_add_u64 v[196:197], s[28:29], 0, v[134:135]
	s_mov_b32 m0, s23
	s_nop 0
	global_load_lds_dwordx4 v[196:197], off
	s_mov_b32 m0, s39
	s_nop 0
	global_load_lds_dwordx4 v[198:199], off
	s_waitcnt vmcnt(8)
	s_waitcnt lgkmcnt(0)
	s_barrier
	s_setprio 1
	s_waitcnt lgkmcnt(0)
	v_mfma_f32_16x16x32_bf16 v[60:63], v[148:151], v[180:183], v[60:63]
	v_mfma_f32_16x16x32_bf16 v[56:59], v[156:159], v[180:183], v[56:59]
	v_mfma_f32_16x16x32_bf16 v[48:51], v[148:151], v[188:191], v[48:51]
	v_mfma_f32_16x16x32_bf16 v[40:43], v[156:159], v[188:191], v[40:43]
	v_mfma_f32_16x16x32_bf16 v[32:35], v[148:151], v[206:209], v[32:35]
	v_mfma_f32_16x16x32_bf16 v[24:27], v[156:159], v[206:209], v[24:27]
	v_mfma_f32_16x16x32_bf16 v[16:19], v[148:151], v[214:217], v[16:19]
	v_mfma_f32_16x16x32_bf16 v[8:11], v[156:159], v[214:217], v[8:11]
	v_mfma_f32_16x16x32_bf16 v[60:63], v[152:155], v[184:187], v[60:63]
	v_mfma_f32_16x16x32_bf16 v[56:59], v[160:163], v[184:187], v[56:59]
	v_mfma_f32_16x16x32_bf16 v[48:51], v[152:155], v[202:205], v[48:51]
	v_mfma_f32_16x16x32_bf16 v[40:43], v[160:163], v[202:205], v[40:43]
	v_mfma_f32_16x16x32_bf16 v[32:35], v[152:155], v[210:213], v[32:35]
	v_mfma_f32_16x16x32_bf16 v[24:27], v[160:163], v[210:213], v[24:27]
	v_mfma_f32_16x16x32_bf16 v[16:19], v[152:155], v[218:221], v[16:19]
	v_mfma_f32_16x16x32_bf16 v[8:11], v[160:163], v[218:221], v[8:11]
	s_setprio 0
	s_setprio 1
	v_mfma_f32_16x16x32_bf16 v[52:55], v[164:167], v[180:183], v[52:55]
	v_mfma_f32_16x16x32_bf16 v[44:47], v[172:175], v[180:183], v[44:47]
	v_mfma_f32_16x16x32_bf16 v[36:39], v[164:167], v[188:191], v[36:39]
	v_mfma_f32_16x16x32_bf16 v[28:31], v[172:175], v[188:191], v[28:31]
	v_mfma_f32_16x16x32_bf16 v[20:23], v[164:167], v[206:209], v[20:23]
	v_mfma_f32_16x16x32_bf16 v[12:15], v[172:175], v[206:209], v[12:15]
	v_mfma_f32_16x16x32_bf16 v[4:7], v[164:167], v[214:217], v[4:7]
	v_mfma_f32_16x16x32_bf16 v[0:3], v[172:175], v[214:217], v[0:3]
	v_mfma_f32_16x16x32_bf16 v[52:55], v[168:171], v[184:187], v[52:55]
	v_mfma_f32_16x16x32_bf16 v[44:47], v[176:179], v[184:187], v[44:47]
	v_mfma_f32_16x16x32_bf16 v[36:39], v[168:171], v[202:205], v[36:39]
	v_mfma_f32_16x16x32_bf16 v[28:31], v[176:179], v[202:205], v[28:31]
	v_mfma_f32_16x16x32_bf16 v[20:23], v[168:171], v[210:213], v[20:23]
	v_mfma_f32_16x16x32_bf16 v[12:15], v[176:179], v[210:213], v[12:15]
	v_mfma_f32_16x16x32_bf16 v[4:7], v[168:171], v[218:221], v[4:7]
	v_mfma_f32_16x16x32_bf16 v[0:3], v[176:179], v[218:221], v[0:3]
	s_setprio 0
	s_barrier
	s_add_i32 s53, 0, 0x18000
	v_add_u32_e32 v147, s53, v141
	s_add_i32 s54, 0, 0x1c000
	ds_read_b128 v[148:151], v147
	ds_read_b128 v[152:155], v147 offset:1024
	ds_read_b128 v[156:159], v147 offset:2048
	ds_read_b128 v[160:163], v147 offset:3072
	v_add_u32_e32 v147, s54, v141
	ds_read_b128 v[164:167], v147
	ds_read_b128 v[168:171], v147 offset:1024
	ds_read_b128 v[172:175], v147 offset:2048
	ds_read_b128 v[176:179], v147 offset:3072
	s_add_u32 s28, s28, 0x40000
	s_addc_u32 s29, s29, 0
	s_mov_b32 m0, s40
	v_lshl_add_u64 v[200:201], s[28:29], 0, v[134:135]
	ds_read_b128 v[180:183], v146 offset:32768
	ds_read_b128 v[184:187], v146 offset:33792
	ds_read_b128 v[188:191], v146 offset:34816
	ds_read_b128 v[202:205], v146 offset:35840
	ds_read_b128 v[206:209], v146 offset:36864
	ds_read_b128 v[210:213], v146 offset:37888
	ds_read_b128 v[214:217], v146 offset:38912
	ds_read_b128 v[218:221], v146 offset:39936
	global_load_lds_dwordx4 v[200:201], off
	v_lshl_add_u64 v[200:201], s[28:29], 0, v[132:133]
	s_mov_b32 m0, s41
	s_nop 0
	global_load_lds_dwordx4 v[200:201], off
	s_waitcnt vmcnt(8)
	s_waitcnt lgkmcnt(0)
	s_barrier
	s_setprio 1
	s_waitcnt lgkmcnt(0)
	v_mfma_f32_16x16x32_bf16 v[126:129], v[148:151], v[180:183], v[126:129]
	v_mfma_f32_16x16x32_bf16 v[122:125], v[156:159], v[180:183], v[122:125]
	v_mfma_f32_16x16x32_bf16 v[114:117], v[148:151], v[188:191], v[114:117]
	v_mfma_f32_16x16x32_bf16 v[106:109], v[156:159], v[188:191], v[106:109]
	v_mfma_f32_16x16x32_bf16 v[98:101], v[148:151], v[206:209], v[98:101]
	v_mfma_f32_16x16x32_bf16 v[88:91], v[156:159], v[206:209], v[88:91]
	v_mfma_f32_16x16x32_bf16 v[80:83], v[148:151], v[214:217], v[80:83]
	v_mfma_f32_16x16x32_bf16 v[72:75], v[156:159], v[214:217], v[72:75]
	v_mfma_f32_16x16x32_bf16 v[126:129], v[152:155], v[184:187], v[126:129]
	v_mfma_f32_16x16x32_bf16 v[122:125], v[160:163], v[184:187], v[122:125]
	v_mfma_f32_16x16x32_bf16 v[114:117], v[152:155], v[202:205], v[114:117]
	v_mfma_f32_16x16x32_bf16 v[106:109], v[160:163], v[202:205], v[106:109]
	v_mfma_f32_16x16x32_bf16 v[98:101], v[152:155], v[210:213], v[98:101]
	v_mfma_f32_16x16x32_bf16 v[88:91], v[160:163], v[210:213], v[88:91]
	v_mfma_f32_16x16x32_bf16 v[80:83], v[152:155], v[218:221], v[80:83]
	v_mfma_f32_16x16x32_bf16 v[72:75], v[160:163], v[218:221], v[72:75]
	s_setprio 0
	s_setprio 1
	v_mfma_f32_16x16x32_bf16 v[118:121], v[164:167], v[180:183], v[118:121]
	v_mfma_f32_16x16x32_bf16 v[110:113], v[172:175], v[180:183], v[110:113]
	v_mfma_f32_16x16x32_bf16 v[102:105], v[164:167], v[188:191], v[102:105]
	v_mfma_f32_16x16x32_bf16 v[92:95], v[172:175], v[188:191], v[92:95]
	v_mfma_f32_16x16x32_bf16 v[84:87], v[164:167], v[206:209], v[84:87]
	v_mfma_f32_16x16x32_bf16 v[76:79], v[172:175], v[206:209], v[76:79]
	v_mfma_f32_16x16x32_bf16 v[68:71], v[164:167], v[214:217], v[68:71]
	v_mfma_f32_16x16x32_bf16 v[64:67], v[172:175], v[214:217], v[64:67]
	v_mfma_f32_16x16x32_bf16 v[118:121], v[168:171], v[184:187], v[118:121]
	v_mfma_f32_16x16x32_bf16 v[110:113], v[176:179], v[184:187], v[110:113]
	v_mfma_f32_16x16x32_bf16 v[102:105], v[168:171], v[202:205], v[102:105]
	v_mfma_f32_16x16x32_bf16 v[92:95], v[176:179], v[202:205], v[92:95]
	v_mfma_f32_16x16x32_bf16 v[84:87], v[168:171], v[210:213], v[84:87]
	v_mfma_f32_16x16x32_bf16 v[76:79], v[176:179], v[210:213], v[76:79]
	v_mfma_f32_16x16x32_bf16 v[68:71], v[168:171], v[218:221], v[68:71]
	v_mfma_f32_16x16x32_bf16 v[64:67], v[176:179], v[218:221], v[64:67]
	s_setprio 0
	s_barrier
	s_add_i32 s28, s53, s38
	v_lshl_add_u64 v[192:193], v[192:193], 0, s[64:65]
	s_mov_b32 m0, s28
	ds_read_b128 v[180:183], v146 offset:49152
	ds_read_b128 v[184:187], v146 offset:50176
	ds_read_b128 v[188:191], v146 offset:51200
	ds_read_b128 v[202:205], v146 offset:52224
	ds_read_b128 v[206:209], v146 offset:53248
	ds_read_b128 v[210:213], v146 offset:54272
	ds_read_b128 v[214:217], v146 offset:55296
	ds_read_b128 v[218:221], v146 offset:56320
	global_load_lds_dwordx4 v[192:193], off
	s_add_i32 m0, s28, 0x2000
	s_add_u32 s26, s26, 0x40080
	v_lshl_add_u64 v[192:193], v[194:195], 0, s[64:65]
	s_addc_u32 s27, s27, 0
	s_add_i32 s28, s54, s38
	global_load_lds_dwordx4 v[192:193], off
	v_lshl_add_u64 v[192:193], s[26:27], 0, v[96:97]
	s_mov_b32 m0, s28
	s_nop 0
	global_load_lds_dwordx4 v[192:193], off
	v_lshl_add_u64 v[192:193], s[26:27], 0, v[130:131]
	s_add_i32 m0, s28, 0x2000
	s_nop 0
	global_load_lds_dwordx4 v[192:193], off
	v_lshl_add_u64 v[192:193], v[196:197], 0, s[64:65]
	s_mov_b32 m0, s42
	s_nop 0
	global_load_lds_dwordx4 v[192:193], off
	v_lshl_add_u64 v[192:193], v[198:199], 0, s[64:65]
	s_mov_b32 m0, s43
	s_nop 0
	global_load_lds_dwordx4 v[192:193], off
	s_waitcnt vmcnt(8)
	s_waitcnt lgkmcnt(0)
	s_barrier
	s_setprio 1
	s_waitcnt lgkmcnt(0)
	v_mfma_f32_16x16x32_bf16 v[60:63], v[148:151], v[180:183], v[60:63]
	v_mfma_f32_16x16x32_bf16 v[56:59], v[156:159], v[180:183], v[56:59]
	v_mfma_f32_16x16x32_bf16 v[48:51], v[148:151], v[188:191], v[48:51]
	v_mfma_f32_16x16x32_bf16 v[40:43], v[156:159], v[188:191], v[40:43]
	v_mfma_f32_16x16x32_bf16 v[32:35], v[148:151], v[206:209], v[32:35]
	v_mfma_f32_16x16x32_bf16 v[24:27], v[156:159], v[206:209], v[24:27]
	v_mfma_f32_16x16x32_bf16 v[16:19], v[148:151], v[214:217], v[16:19]
	v_mfma_f32_16x16x32_bf16 v[8:11], v[156:159], v[214:217], v[8:11]
	v_mfma_f32_16x16x32_bf16 v[60:63], v[152:155], v[184:187], v[60:63]
	v_mfma_f32_16x16x32_bf16 v[56:59], v[160:163], v[184:187], v[56:59]
	v_mfma_f32_16x16x32_bf16 v[48:51], v[152:155], v[202:205], v[48:51]
	v_mfma_f32_16x16x32_bf16 v[40:43], v[160:163], v[202:205], v[40:43]
	v_mfma_f32_16x16x32_bf16 v[32:35], v[152:155], v[210:213], v[32:35]
	v_mfma_f32_16x16x32_bf16 v[24:27], v[160:163], v[210:213], v[24:27]
	v_mfma_f32_16x16x32_bf16 v[16:19], v[152:155], v[218:221], v[16:19]
	v_mfma_f32_16x16x32_bf16 v[8:11], v[160:163], v[218:221], v[8:11]
	s_setprio 0
	s_setprio 1
	v_mfma_f32_16x16x32_bf16 v[52:55], v[164:167], v[180:183], v[52:55]
	v_mfma_f32_16x16x32_bf16 v[44:47], v[172:175], v[180:183], v[44:47]
	v_mfma_f32_16x16x32_bf16 v[36:39], v[164:167], v[188:191], v[36:39]
	v_mfma_f32_16x16x32_bf16 v[28:31], v[172:175], v[188:191], v[28:31]
	v_mfma_f32_16x16x32_bf16 v[20:23], v[164:167], v[206:209], v[20:23]
	v_mfma_f32_16x16x32_bf16 v[12:15], v[172:175], v[206:209], v[12:15]
	v_mfma_f32_16x16x32_bf16 v[4:7], v[164:167], v[214:217], v[4:7]
	v_mfma_f32_16x16x32_bf16 v[0:3], v[172:175], v[214:217], v[0:3]
	v_mfma_f32_16x16x32_bf16 v[52:55], v[168:171], v[184:187], v[52:55]
	v_mfma_f32_16x16x32_bf16 v[44:47], v[176:179], v[184:187], v[44:47]
	v_mfma_f32_16x16x32_bf16 v[36:39], v[168:171], v[202:205], v[36:39]
	v_mfma_f32_16x16x32_bf16 v[28:31], v[176:179], v[202:205], v[28:31]
	v_mfma_f32_16x16x32_bf16 v[20:23], v[168:171], v[210:213], v[20:23]
	v_mfma_f32_16x16x32_bf16 v[12:15], v[176:179], v[210:213], v[12:15]
	v_mfma_f32_16x16x32_bf16 v[4:7], v[168:171], v[218:221], v[4:7]
	v_mfma_f32_16x16x32_bf16 v[0:3], v[176:179], v[218:221], v[0:3]
	s_setprio 0
	s_barrier
	s_add_i32 s52, s52, 2
	s_add_u32 s24, s24, 0x100
	s_addc_u32 s25, s25, 0
	s_add_u32 s50, s50, 0x100
	s_addc_u32 s51, s51, 0
	s_cmp_gt_u32 s52, 13
	s_cbranch_scc0 .LBB0_722
.Lpeel_done_722:
	s_and_b64 vcc, exec, s[10:11]
	s_cbranch_vccz .LBB0_725
	s_barrier
.LBB0_725:
	s_bitcmp1_b32 s46, 0
	s_cselect_b64 s[24:25], -1, 0
	s_and_b64 vcc, exec, s[24:25]
	s_cbranch_vccnz .LBB0_727
	s_and_b64 s[24:25], s[12:13], exec
	s_cselect_b32 s15, s22, s47
	v_lshl_or_b32 v148, s15, 8, v143
	v_ashrrev_i32_e32 v149, 31, v148
	v_lshlrev_b64 v[148:149], 6, v[148:149]
	v_lshl_add_u64 v[160:161], s[4:5], 0, v[148:149]
	global_load_dwordx4 v[148:151], v[160:161], off offset:48
	global_load_dwordx4 v[152:155], v[160:161], off offset:32
	global_load_dwordx4 v[156:159], v[160:161], off offset:16
	s_nop 0
	global_load_dwordx4 v[160:163], v[160:161], off
	s_waitcnt vmcnt(0)
	v_add_f32_e32 v152, v152, v153
	v_add_f32_e32 v154, v154, v155
	v_mov_b32_e32 v164, v161
	v_mov_b32_e32 v165, v162
	v_mov_b32_e32 v161, v163
	v_mov_b32_e32 v162, v157
	v_mov_b32_e32 v163, v158
	v_mov_b32_e32 v157, v159
	v_pk_add_f32 v[160:161], v[164:165], v[160:161]
	v_pk_add_f32 v[156:157], v[162:163], v[156:157]
	v_pk_add_f32 v[160:161], v[160:161], v[160:161] op_sel:[0,1] op_sel_hi:[1,0]
	v_pk_add_f32 v[156:157], v[156:157], v[156:157] op_sel:[0,1] op_sel_hi:[1,0]
	v_mov_b32_e32 v161, v148
	v_mov_b32_e32 v157, v149
	v_mov_b32_e32 v153, v150
	v_mov_b32_e32 v155, v151
	v_pk_add_f32 v[148:149], v[160:161], v[156:157]
	v_pk_add_f32 v[150:151], v[152:153], v[154:155]
	s_nop 0
	v_pk_add_f32 v[148:149], v[148:149], v[150:151]
	s_nop 0
	v_add_f32_e32 v147, v148, v149
	v_fmamk_f32 v147, v147, 0x3a800000, v249
	v_rsq_f32_e32 v147, v147
	ds_write_b32 v145, v147
	s_waitcnt lgkmcnt(0)
	s_barrier

.LBB0_860:
	s_add_u32 s48, s20, 0x100
	s_addc_u32 s49, s21, 0
	s_mov_b32 s50, -2
	s_add_u32 s20, s18, 0x100
	s_addc_u32 s21, s19, 0
	s_add_i32 s51, 0, 0x10000
	s_cmp_eq_u32 s50, 2
	s_cselect_b32 s25, s5, s21
	s_cselect_b32 s24, s4, s20
	v_add_u32_e32 v147, s51, v141
	s_cselect_b32 s23, s17, s49
	s_cselect_b32 s22, s16, s48
	s_add_i32 s52, 0, 0x14000
	ds_read_b128 v[148:151], v147
	ds_read_b128 v[152:155], v147 offset:1024
	ds_read_b128 v[156:159], v147 offset:2048
	ds_read_b128 v[160:163], v147 offset:3072
	v_add_u32_e32 v147, s52, v141
	ds_read_b128 v[164:167], v147
	ds_read_b128 v[168:171], v147 offset:1024
	ds_read_b128 v[172:175], v147 offset:2048
	ds_read_b128 v[176:179], v147 offset:3072
	v_lshl_add_u64 v[192:193], s[18:19], 0, v[136:137]
	s_add_i32 m0, s35, 0xc000
	ds_read_b128 v[180:183], v146
	ds_read_b128 v[184:187], v146 offset:1024
	ds_read_b128 v[188:191], v146 offset:2048
	ds_read_b128 v[202:205], v146 offset:3072
	ds_read_b128 v[206:209], v146 offset:4096
	ds_read_b128 v[210:213], v146 offset:5120
	ds_read_b128 v[214:217], v146 offset:6144
	ds_read_b128 v[218:221], v146 offset:7168
	global_load_lds_dwordx4 v[192:193], off
	v_lshl_add_u64 v[192:193], s[18:19], 0, v[138:139]
	s_add_i32 m0, s35, 0xe000
	s_nop 0
	global_load_lds_dwordx4 v[192:193], off
	s_waitcnt vmcnt(8)
	s_waitcnt lgkmcnt(0)
	s_barrier
	s_setprio 1
	s_waitcnt lgkmcnt(0)
	v_mfma_f32_16x16x32_bf16 v[126:129], v[148:151], v[180:183], 0
	v_mfma_f32_16x16x32_bf16 v[122:125], v[156:159], v[180:183], 0
	v_mfma_f32_16x16x32_bf16 v[114:117], v[148:151], v[188:191], 0
	v_mfma_f32_16x16x32_bf16 v[106:109], v[156:159], v[188:191], 0
	v_mfma_f32_16x16x32_bf16 v[98:101], v[148:151], v[206:209], 0
	v_mfma_f32_16x16x32_bf16 v[88:91], v[156:159], v[206:209], 0
	v_mfma_f32_16x16x32_bf16 v[80:83], v[148:151], v[214:217], 0
	v_mfma_f32_16x16x32_bf16 v[72:75], v[156:159], v[214:217], 0
	v_mfma_f32_16x16x32_bf16 v[126:129], v[152:155], v[184:187], v[126:129]
	v_mfma_f32_16x16x32_bf16 v[122:125], v[160:163], v[184:187], v[122:125]
	v_mfma_f32_16x16x32_bf16 v[114:117], v[152:155], v[202:205], v[114:117]
	v_mfma_f32_16x16x32_bf16 v[106:109], v[160:163], v[202:205], v[106:109]
	v_mfma_f32_16x16x32_bf16 v[98:101], v[152:155], v[210:213], v[98:101]
	v_mfma_f32_16x16x32_bf16 v[88:91], v[160:163], v[210:213], v[88:91]
	v_mfma_f32_16x16x32_bf16 v[80:83], v[152:155], v[218:221], v[80:83]
	v_mfma_f32_16x16x32_bf16 v[72:75], v[160:163], v[218:221], v[72:75]
	s_setprio 0
	s_setprio 1
	v_mfma_f32_16x16x32_bf16 v[118:121], v[164:167], v[180:183], 0
	v_mfma_f32_16x16x32_bf16 v[110:113], v[172:175], v[180:183], 0
	v_mfma_f32_16x16x32_bf16 v[102:105], v[164:167], v[188:191], 0
	v_mfma_f32_16x16x32_bf16 v[92:95], v[172:175], v[188:191], 0
	v_mfma_f32_16x16x32_bf16 v[84:87], v[164:167], v[206:209], 0
	v_mfma_f32_16x16x32_bf16 v[76:79], v[172:175], v[206:209], 0
	v_mfma_f32_16x16x32_bf16 v[68:71], v[164:167], v[214:217], 0
	v_mfma_f32_16x16x32_bf16 v[64:67], v[172:175], v[214:217], 0
	v_mfma_f32_16x16x32_bf16 v[118:121], v[168:171], v[184:187], v[118:121]
	v_mfma_f32_16x16x32_bf16 v[110:113], v[176:179], v[184:187], v[110:113]
	v_mfma_f32_16x16x32_bf16 v[102:105], v[168:171], v[202:205], v[102:105]
	v_mfma_f32_16x16x32_bf16 v[92:95], v[176:179], v[202:205], v[92:95]
	v_mfma_f32_16x16x32_bf16 v[84:87], v[168:171], v[210:213], v[84:87]
	v_mfma_f32_16x16x32_bf16 v[76:79], v[176:179], v[210:213], v[76:79]
	v_mfma_f32_16x16x32_bf16 v[68:71], v[168:171], v[218:221], v[68:71]
	v_mfma_f32_16x16x32_bf16 v[64:67], v[176:179], v[218:221], v[64:67]
	s_setprio 0
	s_barrier
	s_add_i32 s18, s51, s34
	v_lshl_add_u64 v[192:193], s[22:23], 0, v[96:97]
	s_mov_b32 m0, s18
	ds_read_b128 v[180:183], v146 offset:16384
	ds_read_b128 v[184:187], v146 offset:17408
	ds_read_b128 v[188:191], v146 offset:18432
	ds_read_b128 v[202:205], v146 offset:19456
	ds_read_b128 v[206:209], v146 offset:20480
	ds_read_b128 v[210:213], v146 offset:21504
	ds_read_b128 v[214:217], v146 offset:22528
	ds_read_b128 v[218:221], v146 offset:23552
	global_load_lds_dwordx4 v[192:193], off
	s_add_i32 m0, s18, 0x2000
	s_add_u32 s18, s22, 0x18000
	v_lshl_add_u64 v[194:195], s[22:23], 0, v[130:131]
	s_addc_u32 s19, s23, 0
	s_add_i32 s51, s52, s34
	global_load_lds_dwordx4 v[194:195], off
	v_lshl_add_u64 v[196:197], s[18:19], 0, v[96:97]
	s_mov_b32 m0, s51
	v_lshl_add_u64 v[198:199], s[24:25], 0, v[132:133]
	global_load_lds_dwordx4 v[196:197], off
	v_lshl_add_u64 v[196:197], s[18:19], 0, v[130:131]
	s_add_i32 m0, s51, 0x2000
	s_nop 0
	global_load_lds_dwordx4 v[196:197], off
	v_lshl_add_u64 v[196:197], s[24:25], 0, v[134:135]
	s_mov_b32 m0, s35
	s_nop 0
	global_load_lds_dwordx4 v[196:197], off
	s_mov_b32 m0, s36
	s_nop 0
	global_load_lds_dwordx4 v[198:199], off
	s_waitcnt vmcnt(8)
	s_waitcnt lgkmcnt(0)
	s_barrier
	s_setprio 1
	s_waitcnt lgkmcnt(0)
	v_mfma_f32_16x16x32_bf16 v[60:63], v[148:151], v[180:183], 0
	v_mfma_f32_16x16x32_bf16 v[56:59], v[156:159], v[180:183], 0
	v_mfma_f32_16x16x32_bf16 v[48:51], v[148:151], v[188:191], 0
	v_mfma_f32_16x16x32_bf16 v[40:43], v[156:159], v[188:191], 0
	v_mfma_f32_16x16x32_bf16 v[32:35], v[148:151], v[206:209], 0
	v_mfma_f32_16x16x32_bf16 v[24:27], v[156:159], v[206:209], 0
	v_mfma_f32_16x16x32_bf16 v[16:19], v[148:151], v[214:217], 0
	v_mfma_f32_16x16x32_bf16 v[8:11], v[156:159], v[214:217], 0
	v_mfma_f32_16x16x32_bf16 v[60:63], v[152:155], v[184:187], v[60:63]
	v_mfma_f32_16x16x32_bf16 v[56:59], v[160:163], v[184:187], v[56:59]
	v_mfma_f32_16x16x32_bf16 v[48:51], v[152:155], v[202:205], v[48:51]
	v_mfma_f32_16x16x32_bf16 v[40:43], v[160:163], v[202:205], v[40:43]
	v_mfma_f32_16x16x32_bf16 v[32:35], v[152:155], v[210:213], v[32:35]
	v_mfma_f32_16x16x32_bf16 v[24:27], v[160:163], v[210:213], v[24:27]
	v_mfma_f32_16x16x32_bf16 v[16:19], v[152:155], v[218:221], v[16:19]
	v_mfma_f32_16x16x32_bf16 v[8:11], v[160:163], v[218:221], v[8:11]
	s_setprio 0
	s_setprio 1
	v_mfma_f32_16x16x32_bf16 v[52:55], v[164:167], v[180:183], 0
	v_mfma_f32_16x16x32_bf16 v[44:47], v[172:175], v[180:183], 0
	v_mfma_f32_16x16x32_bf16 v[36:39], v[164:167], v[188:191], 0
	v_mfma_f32_16x16x32_bf16 v[28:31], v[172:175], v[188:191], 0
	v_mfma_f32_16x16x32_bf16 v[20:23], v[164:167], v[206:209], 0
	v_mfma_f32_16x16x32_bf16 v[12:15], v[172:175], v[206:209], 0
	v_mfma_f32_16x16x32_bf16 v[4:7], v[164:167], v[214:217], 0
	v_mfma_f32_16x16x32_bf16 v[0:3], v[172:175], v[214:217], 0
	v_mfma_f32_16x16x32_bf16 v[52:55], v[168:171], v[184:187], v[52:55]
	v_mfma_f32_16x16x32_bf16 v[44:47], v[176:179], v[184:187], v[44:47]
	v_mfma_f32_16x16x32_bf16 v[36:39], v[168:171], v[202:205], v[36:39]
	v_mfma_f32_16x16x32_bf16 v[28:31], v[176:179], v[202:205], v[28:31]
	v_mfma_f32_16x16x32_bf16 v[20:23], v[168:171], v[210:213], v[20:23]
	v_mfma_f32_16x16x32_bf16 v[12:15], v[176:179], v[210:213], v[12:15]
	v_mfma_f32_16x16x32_bf16 v[4:7], v[168:171], v[218:221], v[4:7]
	v_mfma_f32_16x16x32_bf16 v[0:3], v[176:179], v[218:221], v[0:3]
	s_setprio 0
	s_barrier
	s_add_i32 s51, 0, 0x18000
	v_add_u32_e32 v147, s51, v141
	s_add_i32 s52, 0, 0x1c000
	ds_read_b128 v[148:151], v147
	ds_read_b128 v[152:155], v147 offset:1024
	ds_read_b128 v[156:159], v147 offset:2048
	ds_read_b128 v[160:163], v147 offset:3072
	v_add_u32_e32 v147, s52, v141
	ds_read_b128 v[164:167], v147
	ds_read_b128 v[168:171], v147 offset:1024
	ds_read_b128 v[172:175], v147 offset:2048
	ds_read_b128 v[176:179], v147 offset:3072
	s_add_u32 s18, s24, 0x50000
	s_addc_u32 s19, s25, 0
	s_mov_b32 m0, s37
	v_lshl_add_u64 v[200:201], s[18:19], 0, v[134:135]
	ds_read_b128 v[180:183], v146 offset:32768
	ds_read_b128 v[184:187], v146 offset:33792
	ds_read_b128 v[188:191], v146 offset:34816
	ds_read_b128 v[202:205], v146 offset:35840
	ds_read_b128 v[206:209], v146 offset:36864
	ds_read_b128 v[210:213], v146 offset:37888
	ds_read_b128 v[214:217], v146 offset:38912
	ds_read_b128 v[218:221], v146 offset:39936
	global_load_lds_dwordx4 v[200:201], off
	v_lshl_add_u64 v[200:201], s[18:19], 0, v[132:133]
	s_mov_b32 m0, s38
	s_nop 0
	global_load_lds_dwordx4 v[200:201], off
	s_waitcnt vmcnt(8)
	s_waitcnt lgkmcnt(0)
	s_barrier
	s_setprio 1
	s_waitcnt lgkmcnt(0)
	v_mfma_f32_16x16x32_bf16 v[126:129], v[148:151], v[180:183], v[126:129]
	v_mfma_f32_16x16x32_bf16 v[122:125], v[156:159], v[180:183], v[122:125]
	v_mfma_f32_16x16x32_bf16 v[114:117], v[148:151], v[188:191], v[114:117]
	v_mfma_f32_16x16x32_bf16 v[106:109], v[156:159], v[188:191], v[106:109]
	v_mfma_f32_16x16x32_bf16 v[98:101], v[148:151], v[206:209], v[98:101]
	v_mfma_f32_16x16x32_bf16 v[88:91], v[156:159], v[206:209], v[88:91]
	v_mfma_f32_16x16x32_bf16 v[80:83], v[148:151], v[214:217], v[80:83]
	v_mfma_f32_16x16x32_bf16 v[72:75], v[156:159], v[214:217], v[72:75]
	v_mfma_f32_16x16x32_bf16 v[126:129], v[152:155], v[184:187], v[126:129]
	v_mfma_f32_16x16x32_bf16 v[122:125], v[160:163], v[184:187], v[122:125]
	v_mfma_f32_16x16x32_bf16 v[114:117], v[152:155], v[202:205], v[114:117]
	v_mfma_f32_16x16x32_bf16 v[106:109], v[160:163], v[202:205], v[106:109]
	v_mfma_f32_16x16x32_bf16 v[98:101], v[152:155], v[210:213], v[98:101]
	v_mfma_f32_16x16x32_bf16 v[88:91], v[160:163], v[210:213], v[88:91]
	v_mfma_f32_16x16x32_bf16 v[80:83], v[152:155], v[218:221], v[80:83]
	v_mfma_f32_16x16x32_bf16 v[72:75], v[160:163], v[218:221], v[72:75]
	s_setprio 0
	s_setprio 1
	v_mfma_f32_16x16x32_bf16 v[118:121], v[164:167], v[180:183], v[118:121]
	v_mfma_f32_16x16x32_bf16 v[110:113], v[172:175], v[180:183], v[110:113]
	v_mfma_f32_16x16x32_bf16 v[102:105], v[164:167], v[188:191], v[102:105]
	v_mfma_f32_16x16x32_bf16 v[92:95], v[172:175], v[188:191], v[92:95]
	v_mfma_f32_16x16x32_bf16 v[84:87], v[164:167], v[206:209], v[84:87]
	v_mfma_f32_16x16x32_bf16 v[76:79], v[172:175], v[206:209], v[76:79]
	v_mfma_f32_16x16x32_bf16 v[68:71], v[164:167], v[214:217], v[68:71]
	v_mfma_f32_16x16x32_bf16 v[64:67], v[172:175], v[214:217], v[64:67]
	v_mfma_f32_16x16x32_bf16 v[118:121], v[168:171], v[184:187], v[118:121]
	v_mfma_f32_16x16x32_bf16 v[110:113], v[176:179], v[184:187], v[110:113]
	v_mfma_f32_16x16x32_bf16 v[102:105], v[168:171], v[202:205], v[102:105]
	v_mfma_f32_16x16x32_bf16 v[92:95], v[176:179], v[202:205], v[92:95]
	v_mfma_f32_16x16x32_bf16 v[84:87], v[168:171], v[210:213], v[84:87]
	v_mfma_f32_16x16x32_bf16 v[76:79], v[176:179], v[210:213], v[76:79]
	v_mfma_f32_16x16x32_bf16 v[68:71], v[168:171], v[218:221], v[68:71]
	v_mfma_f32_16x16x32_bf16 v[64:67], v[176:179], v[218:221], v[64:67]
	s_setprio 0
	s_barrier
	s_add_i32 s18, s51, s34
	v_lshl_add_u64 v[192:193], v[192:193], 0, s[64:65]
	s_mov_b32 m0, s18
	ds_read_b128 v[180:183], v146 offset:49152
	ds_read_b128 v[184:187], v146 offset:50176
	ds_read_b128 v[188:191], v146 offset:51200
	ds_read_b128 v[202:205], v146 offset:52224
	ds_read_b128 v[206:209], v146 offset:53248
	ds_read_b128 v[210:213], v146 offset:54272
	ds_read_b128 v[214:217], v146 offset:55296
	ds_read_b128 v[218:221], v146 offset:56320
	global_load_lds_dwordx4 v[192:193], off
	s_add_i32 m0, s18, 0x2000
	s_add_u32 s18, s22, 0x18080
	v_lshl_add_u64 v[192:193], v[194:195], 0, s[64:65]
	s_addc_u32 s19, s23, 0
	s_add_i32 s22, s52, s34
	global_load_lds_dwordx4 v[192:193], off
	v_lshl_add_u64 v[192:193], s[18:19], 0, v[96:97]
	s_mov_b32 m0, s22
	s_nop 0
	global_load_lds_dwordx4 v[192:193], off
	v_lshl_add_u64 v[192:193], s[18:19], 0, v[130:131]
	s_add_i32 m0, s22, 0x2000
	s_nop 0
	global_load_lds_dwordx4 v[192:193], off
	v_lshl_add_u64 v[192:193], v[196:197], 0, s[64:65]
	s_mov_b32 m0, s39
	s_nop 0
	global_load_lds_dwordx4 v[192:193], off
	v_lshl_add_u64 v[192:193], v[198:199], 0, s[64:65]
	s_mov_b32 m0, s40
	s_nop 0
	global_load_lds_dwordx4 v[192:193], off
	s_waitcnt vmcnt(8)
	s_waitcnt lgkmcnt(0)
	s_barrier
	s_setprio 1
	s_waitcnt lgkmcnt(0)
	v_mfma_f32_16x16x32_bf16 v[60:63], v[148:151], v[180:183], v[60:63]
	v_mfma_f32_16x16x32_bf16 v[56:59], v[156:159], v[180:183], v[56:59]
	v_mfma_f32_16x16x32_bf16 v[48:51], v[148:151], v[188:191], v[48:51]
	v_mfma_f32_16x16x32_bf16 v[40:43], v[156:159], v[188:191], v[40:43]
	v_mfma_f32_16x16x32_bf16 v[32:35], v[148:151], v[206:209], v[32:35]
	v_mfma_f32_16x16x32_bf16 v[24:27], v[156:159], v[206:209], v[24:27]
	v_mfma_f32_16x16x32_bf16 v[16:19], v[148:151], v[214:217], v[16:19]
	v_mfma_f32_16x16x32_bf16 v[8:11], v[156:159], v[214:217], v[8:11]
	v_mfma_f32_16x16x32_bf16 v[60:63], v[152:155], v[184:187], v[60:63]
	v_mfma_f32_16x16x32_bf16 v[56:59], v[160:163], v[184:187], v[56:59]
	v_mfma_f32_16x16x32_bf16 v[48:51], v[152:155], v[202:205], v[48:51]
	v_mfma_f32_16x16x32_bf16 v[40:43], v[160:163], v[202:205], v[40:43]
	v_mfma_f32_16x16x32_bf16 v[32:35], v[152:155], v[210:213], v[32:35]
	v_mfma_f32_16x16x32_bf16 v[24:27], v[160:163], v[210:213], v[24:27]
	v_mfma_f32_16x16x32_bf16 v[16:19], v[152:155], v[218:221], v[16:19]
	v_mfma_f32_16x16x32_bf16 v[8:11], v[160:163], v[218:221], v[8:11]
	s_setprio 0
	s_setprio 1
	v_mfma_f32_16x16x32_bf16 v[52:55], v[164:167], v[180:183], v[52:55]
	v_mfma_f32_16x16x32_bf16 v[44:47], v[172:175], v[180:183], v[44:47]
	v_mfma_f32_16x16x32_bf16 v[36:39], v[164:167], v[188:191], v[36:39]
	v_mfma_f32_16x16x32_bf16 v[28:31], v[172:175], v[188:191], v[28:31]
	v_mfma_f32_16x16x32_bf16 v[20:23], v[164:167], v[206:209], v[20:23]
	v_mfma_f32_16x16x32_bf16 v[12:15], v[172:175], v[206:209], v[12:15]
	v_mfma_f32_16x16x32_bf16 v[4:7], v[164:167], v[214:217], v[4:7]
	v_mfma_f32_16x16x32_bf16 v[0:3], v[172:175], v[214:217], v[0:3]
	v_mfma_f32_16x16x32_bf16 v[52:55], v[168:171], v[184:187], v[52:55]
	v_mfma_f32_16x16x32_bf16 v[44:47], v[176:179], v[184:187], v[44:47]
	v_mfma_f32_16x16x32_bf16 v[36:39], v[168:171], v[202:205], v[36:39]
	v_mfma_f32_16x16x32_bf16 v[28:31], v[176:179], v[202:205], v[28:31]
	v_mfma_f32_16x16x32_bf16 v[20:23], v[168:171], v[210:213], v[20:23]
	v_mfma_f32_16x16x32_bf16 v[12:15], v[176:179], v[210:213], v[12:15]
	v_mfma_f32_16x16x32_bf16 v[4:7], v[168:171], v[218:221], v[4:7]
	v_mfma_f32_16x16x32_bf16 v[0:3], v[176:179], v[218:221], v[0:3]
	s_setprio 0
	s_barrier
	s_add_i32 s50, s50, 2
	s_add_u32 s48, s48, 0x100
	s_addc_u32 s49, s49, 0
	s_cmp_gt_u32 s50, 3
	s_mov_b64 s[18:19], s[20:21]
	s_cbranch_scc1 .Lpeel_done_861

.LBB0_1236:
	s_ashr_i32 s17, s16, 31
	s_lshl_b64 s[18:19], s[16:17], 19
	s_add_u32 s18, s35, s18
	s_addc_u32 s19, s36, s19
	s_and_b64 s[20:21], s[4:5], exec
	s_cselect_b32 s17, s19, s27
	s_cselect_b32 s23, s18, s26
	s_ashr_i32 s15, s14, 31
	s_lshl_b64 s[20:21], s[14:15], 19
	s_add_u32 s20, s37, s20
	s_addc_u32 s21, s38, s21
	s_and_b64 s[30:31], s[4:5], exec
	s_cselect_b32 s15, s21, s29
	s_cselect_b32 s25, s20, s28
	s_add_u32 s26, s26, 0x40080
	s_addc_u32 s27, s27, 0
	s_add_u32 s49, s28, 0x100
	s_addc_u32 s50, s29, 0
	s_mov_b32 s51, -2
	s_waitcnt vmcnt(0)
	s_add_u32 s28, s26, 0xfffc0080
	s_addc_u32 s29, s27, -1
	s_add_i32 s52, 0, 0x10000
	s_cmp_eq_u32 s51, 12
	s_cselect_b32 s31, s17, s29
	s_cselect_b32 s30, s23, s28
	s_cselect_b32 s29, s15, s50
	s_cselect_b32 s28, s25, s49
	s_add_i32 s54, 0, 0x14000
	v_add_u32_e32 v134, s52, v245
	v_add_u32_e32 v150, s54, v245
	ds_read_b128 v[122:125], v134
	ds_read_b128 v[126:129], v134 offset:1024
	ds_read_b128 v[130:133], v134 offset:2048
	ds_read_b128 v[134:137], v134 offset:3072
	ds_read_b128 v[138:141], v150
	ds_read_b128 v[142:145], v150 offset:1024
	ds_read_b128 v[146:149], v150 offset:2048
	ds_read_b128 v[150:153], v150 offset:3072
	v_lshl_add_u64 v[194:195], s[26:27], 0, v[204:205]
	s_add_i32 m0, s40, 0xc000
	ds_read_b128 v[162:165], v199
	ds_read_b128 v[166:169], v199 offset:1024
	ds_read_b128 v[170:173], v199 offset:2048
	ds_read_b128 v[174:177], v199 offset:3072
	ds_read_b128 v[178:181], v199 offset:4096
	ds_read_b128 v[182:185], v199 offset:5120
	ds_read_b128 v[186:189], v199 offset:6144
	ds_read_b128 v[208:211], v199 offset:7168
	global_load_lds_dwordx4 v[194:195], off
	v_lshl_add_u64 v[194:195], s[26:27], 0, v[206:207]
	s_add_i32 m0, s40, 0xe000
	s_nop 0
	global_load_lds_dwordx4 v[194:195], off
	s_waitcnt vmcnt(8)
	s_waitcnt lgkmcnt(0)
	s_barrier
	s_setprio 1
	s_waitcnt lgkmcnt(0)
	v_mfma_f32_16x16x32_bf16 v[158:161], v[122:125], v[162:165], 0
	v_mfma_f32_16x16x32_bf16 v[154:157], v[130:133], v[162:165], 0
	v_mfma_f32_16x16x32_bf16 v[110:113], v[122:125], v[170:173], 0
	v_mfma_f32_16x16x32_bf16 v[106:109], v[130:133], v[170:173], 0
	v_mfma_f32_16x16x32_bf16 v[92:95], v[122:125], v[178:181], 0
	v_mfma_f32_16x16x32_bf16 v[88:91], v[130:133], v[178:181], 0
	v_mfma_f32_16x16x32_bf16 v[76:79], v[122:125], v[186:189], 0
	v_mfma_f32_16x16x32_bf16 v[72:75], v[130:133], v[186:189], 0
	v_mfma_f32_16x16x32_bf16 v[158:161], v[126:129], v[166:169], v[158:161]
	v_mfma_f32_16x16x32_bf16 v[154:157], v[134:137], v[166:169], v[154:157]
	v_mfma_f32_16x16x32_bf16 v[110:113], v[126:129], v[174:177], v[110:113]
	v_mfma_f32_16x16x32_bf16 v[106:109], v[134:137], v[174:177], v[106:109]
	v_mfma_f32_16x16x32_bf16 v[92:95], v[126:129], v[182:185], v[92:95]
	v_mfma_f32_16x16x32_bf16 v[88:91], v[134:137], v[182:185], v[88:91]
	v_mfma_f32_16x16x32_bf16 v[76:79], v[126:129], v[208:211], v[76:79]
	v_mfma_f32_16x16x32_bf16 v[72:75], v[134:137], v[208:211], v[72:75]
	s_setprio 0
	s_setprio 1
	v_mfma_f32_16x16x32_bf16 v[118:121], v[138:141], v[162:165], 0
	v_mfma_f32_16x16x32_bf16 v[114:117], v[146:149], v[162:165], 0
	v_mfma_f32_16x16x32_bf16 v[102:105], v[138:141], v[170:173], 0
	v_mfma_f32_16x16x32_bf16 v[98:101], v[146:149], v[170:173], 0
	v_mfma_f32_16x16x32_bf16 v[84:87], v[138:141], v[178:181], 0
	v_mfma_f32_16x16x32_bf16 v[80:83], v[146:149], v[178:181], 0
	v_mfma_f32_16x16x32_bf16 v[68:71], v[138:141], v[186:189], 0
	v_mfma_f32_16x16x32_bf16 v[64:67], v[146:149], v[186:189], 0
	v_mfma_f32_16x16x32_bf16 v[118:121], v[142:145], v[166:169], v[118:121]
	v_mfma_f32_16x16x32_bf16 v[114:117], v[150:153], v[166:169], v[114:117]
	v_mfma_f32_16x16x32_bf16 v[102:105], v[142:145], v[174:177], v[102:105]
	v_mfma_f32_16x16x32_bf16 v[98:101], v[150:153], v[174:177], v[98:101]
	v_mfma_f32_16x16x32_bf16 v[84:87], v[142:145], v[182:185], v[84:87]
	v_mfma_f32_16x16x32_bf16 v[80:83], v[150:153], v[182:185], v[80:83]
	v_mfma_f32_16x16x32_bf16 v[68:71], v[142:145], v[208:211], v[68:71]
	v_mfma_f32_16x16x32_bf16 v[64:67], v[150:153], v[208:211], v[64:67]
	s_setprio 0
	s_barrier
	s_add_i32 s52, s52, s39
	v_lshl_add_u64 v[194:195], s[28:29], 0, v[96:97]
	s_mov_b32 m0, s52
	ds_read_b128 v[162:165], v199 offset:16384
	ds_read_b128 v[166:169], v199 offset:17408
	ds_read_b128 v[170:173], v199 offset:18432
	ds_read_b128 v[174:177], v199 offset:19456
	ds_read_b128 v[178:181], v199 offset:20480
	ds_read_b128 v[182:185], v199 offset:21504
	ds_read_b128 v[186:189], v199 offset:22528
	ds_read_b128 v[208:211], v199 offset:23552
	global_load_lds_dwordx4 v[194:195], off
	s_add_i32 m0, s52, 0x2000
	s_add_u32 s52, s28, 0x40000
	v_lshl_add_u64 v[196:197], s[28:29], 0, v[202:203]
	s_addc_u32 s53, s29, 0
	s_add_i32 s54, s54, s39
	global_load_lds_dwordx4 v[196:197], off
	v_lshl_add_u64 v[200:201], s[52:53], 0, v[96:97]
	s_mov_b32 m0, s54
	v_lshl_add_u64 v[212:213], s[30:31], 0, v[192:193]
	global_load_lds_dwordx4 v[200:201], off
	v_lshl_add_u64 v[200:201], s[52:53], 0, v[202:203]
	s_add_i32 m0, s54, 0x2000
	s_nop 0
	global_load_lds_dwordx4 v[200:201], off
	v_lshl_add_u64 v[200:201], s[30:31], 0, v[190:191]
	s_mov_b32 m0, s40
	s_nop 0
	global_load_lds_dwordx4 v[200:201], off
	s_mov_b32 m0, s41
	s_nop 0
	global_load_lds_dwordx4 v[212:213], off
	s_waitcnt vmcnt(8)
	s_waitcnt lgkmcnt(0)
	s_barrier
	s_setprio 1
	s_waitcnt lgkmcnt(0)
	v_mfma_f32_16x16x32_bf16 v[60:63], v[122:125], v[162:165], 0
	v_mfma_f32_16x16x32_bf16 v[56:59], v[130:133], v[162:165], 0
	v_mfma_f32_16x16x32_bf16 v[44:47], v[122:125], v[170:173], 0
	v_mfma_f32_16x16x32_bf16 v[40:43], v[130:133], v[170:173], 0
	v_mfma_f32_16x16x32_bf16 v[28:31], v[122:125], v[178:181], 0
	v_mfma_f32_16x16x32_bf16 v[24:27], v[130:133], v[178:181], 0
	v_mfma_f32_16x16x32_bf16 v[12:15], v[122:125], v[186:189], 0
	v_mfma_f32_16x16x32_bf16 v[8:11], v[130:133], v[186:189], 0
	v_mfma_f32_16x16x32_bf16 v[60:63], v[126:129], v[166:169], v[60:63]
	v_mfma_f32_16x16x32_bf16 v[56:59], v[134:137], v[166:169], v[56:59]
	v_mfma_f32_16x16x32_bf16 v[44:47], v[126:129], v[174:177], v[44:47]
	v_mfma_f32_16x16x32_bf16 v[40:43], v[134:137], v[174:177], v[40:43]
	v_mfma_f32_16x16x32_bf16 v[28:31], v[126:129], v[182:185], v[28:31]
	v_mfma_f32_16x16x32_bf16 v[24:27], v[134:137], v[182:185], v[24:27]
	v_mfma_f32_16x16x32_bf16 v[12:15], v[126:129], v[208:211], v[12:15]
	v_mfma_f32_16x16x32_bf16 v[8:11], v[134:137], v[208:211], v[8:11]
	s_setprio 0
	s_setprio 1
	v_mfma_f32_16x16x32_bf16 v[52:55], v[138:141], v[162:165], 0
	v_mfma_f32_16x16x32_bf16 v[48:51], v[146:149], v[162:165], 0
	v_mfma_f32_16x16x32_bf16 v[36:39], v[138:141], v[170:173], 0
	v_mfma_f32_16x16x32_bf16 v[32:35], v[146:149], v[170:173], 0
	v_mfma_f32_16x16x32_bf16 v[20:23], v[138:141], v[178:181], 0
	v_mfma_f32_16x16x32_bf16 v[16:19], v[146:149], v[178:181], 0
	v_mfma_f32_16x16x32_bf16 v[4:7], v[138:141], v[186:189], 0
	v_mfma_f32_16x16x32_bf16 v[0:3], v[146:149], v[186:189], 0
	v_mfma_f32_16x16x32_bf16 v[52:55], v[142:145], v[166:169], v[52:55]
	v_mfma_f32_16x16x32_bf16 v[48:51], v[150:153], v[166:169], v[48:51]
	v_mfma_f32_16x16x32_bf16 v[36:39], v[142:145], v[174:177], v[36:39]
	v_mfma_f32_16x16x32_bf16 v[32:35], v[150:153], v[174:177], v[32:35]
	v_mfma_f32_16x16x32_bf16 v[20:23], v[142:145], v[182:185], v[20:23]
	v_mfma_f32_16x16x32_bf16 v[16:19], v[150:153], v[182:185], v[16:19]
	v_mfma_f32_16x16x32_bf16 v[4:7], v[142:145], v[208:211], v[4:7]
	v_mfma_f32_16x16x32_bf16 v[0:3], v[150:153], v[208:211], v[0:3]
	s_setprio 0
	s_barrier
	s_add_i32 s52, 0, 0x18000
	s_add_i32 s53, 0, 0x1c000
	v_add_u32_e32 v134, s52, v245
	v_add_u32_e32 v150, s53, v245
	ds_read_b128 v[122:125], v134
	ds_read_b128 v[126:129], v134 offset:1024
	ds_read_b128 v[130:133], v134 offset:2048
	ds_read_b128 v[134:137], v134 offset:3072
	ds_read_b128 v[138:141], v150
	ds_read_b128 v[142:145], v150 offset:1024
	ds_read_b128 v[146:149], v150 offset:2048
	ds_read_b128 v[150:153], v150 offset:3072
	s_add_u32 s30, s30, 0x40000
	s_addc_u32 s31, s31, 0
	s_mov_b32 m0, s42
	v_lshl_add_u64 v[214:215], s[30:31], 0, v[190:191]
	ds_read_b128 v[162:165], v199 offset:32768
	ds_read_b128 v[166:169], v199 offset:33792
	ds_read_b128 v[170:173], v199 offset:34816
	ds_read_b128 v[174:177], v199 offset:35840
	ds_read_b128 v[178:181], v199 offset:36864
	ds_read_b128 v[182:185], v199 offset:37888
	ds_read_b128 v[186:189], v199 offset:38912
	ds_read_b128 v[208:211], v199 offset:39936
	global_load_lds_dwordx4 v[214:215], off
	v_lshl_add_u64 v[214:215], s[30:31], 0, v[192:193]
	s_mov_b32 m0, s43
	s_nop 0
	global_load_lds_dwordx4 v[214:215], off
	s_waitcnt vmcnt(8)
	s_waitcnt lgkmcnt(0)
	s_barrier
	s_setprio 1
	s_waitcnt lgkmcnt(0)
	v_mfma_f32_16x16x32_bf16 v[158:161], v[122:125], v[162:165], v[158:161]
	v_mfma_f32_16x16x32_bf16 v[154:157], v[130:133], v[162:165], v[154:157]
	v_mfma_f32_16x16x32_bf16 v[110:113], v[122:125], v[170:173], v[110:113]
	v_mfma_f32_16x16x32_bf16 v[106:109], v[130:133], v[170:173], v[106:109]
	v_mfma_f32_16x16x32_bf16 v[92:95], v[122:125], v[178:181], v[92:95]
	v_mfma_f32_16x16x32_bf16 v[88:91], v[130:133], v[178:181], v[88:91]
	v_mfma_f32_16x16x32_bf16 v[76:79], v[122:125], v[186:189], v[76:79]
	v_mfma_f32_16x16x32_bf16 v[72:75], v[130:133], v[186:189], v[72:75]
	v_mfma_f32_16x16x32_bf16 v[158:161], v[126:129], v[166:169], v[158:161]
	v_mfma_f32_16x16x32_bf16 v[154:157], v[134:137], v[166:169], v[154:157]
	v_mfma_f32_16x16x32_bf16 v[110:113], v[126:129], v[174:177], v[110:113]
	v_mfma_f32_16x16x32_bf16 v[106:109], v[134:137], v[174:177], v[106:109]
	v_mfma_f32_16x16x32_bf16 v[92:95], v[126:129], v[182:185], v[92:95]
	v_mfma_f32_16x16x32_bf16 v[88:91], v[134:137], v[182:185], v[88:91]
	v_mfma_f32_16x16x32_bf16 v[76:79], v[126:129], v[208:211], v[76:79]
	v_mfma_f32_16x16x32_bf16 v[72:75], v[134:137], v[208:211], v[72:75]
	s_setprio 0
	s_setprio 1
	v_mfma_f32_16x16x32_bf16 v[118:121], v[138:141], v[162:165], v[118:121]
	v_mfma_f32_16x16x32_bf16 v[114:117], v[146:149], v[162:165], v[114:117]
	v_mfma_f32_16x16x32_bf16 v[102:105], v[138:141], v[170:173], v[102:105]
	v_mfma_f32_16x16x32_bf16 v[98:101], v[146:149], v[170:173], v[98:101]
	v_mfma_f32_16x16x32_bf16 v[84:87], v[138:141], v[178:181], v[84:87]
	v_mfma_f32_16x16x32_bf16 v[80:83], v[146:149], v[178:181], v[80:83]
	v_mfma_f32_16x16x32_bf16 v[68:71], v[138:141], v[186:189], v[68:71]
	v_mfma_f32_16x16x32_bf16 v[64:67], v[146:149], v[186:189], v[64:67]
	v_mfma_f32_16x16x32_bf16 v[118:121], v[142:145], v[166:169], v[118:121]
	v_mfma_f32_16x16x32_bf16 v[114:117], v[150:153], v[166:169], v[114:117]
	v_mfma_f32_16x16x32_bf16 v[102:105], v[142:145], v[174:177], v[102:105]
	v_mfma_f32_16x16x32_bf16 v[98:101], v[150:153], v[174:177], v[98:101]
	v_mfma_f32_16x16x32_bf16 v[84:87], v[142:145], v[182:185], v[84:87]
	v_mfma_f32_16x16x32_bf16 v[80:83], v[150:153], v[182:185], v[80:83]
	v_mfma_f32_16x16x32_bf16 v[68:71], v[142:145], v[208:211], v[68:71]
	v_mfma_f32_16x16x32_bf16 v[64:67], v[150:153], v[208:211], v[64:67]
	s_setprio 0
	s_barrier
	s_add_i32 s30, s52, s39
	v_lshl_add_u64 v[194:195], v[194:195], 0, s[64:65]
	s_mov_b32 m0, s30
	ds_read_b128 v[162:165], v199 offset:49152
	ds_read_b128 v[166:169], v199 offset:50176
	ds_read_b128 v[170:173], v199 offset:51200
	ds_read_b128 v[174:177], v199 offset:52224
	ds_read_b128 v[178:181], v199 offset:53248
	ds_read_b128 v[182:185], v199 offset:54272
	ds_read_b128 v[186:189], v199 offset:55296
	ds_read_b128 v[208:211], v199 offset:56320
	global_load_lds_dwordx4 v[194:195], off
	s_add_i32 m0, s30, 0x2000
	s_add_u32 s28, s28, 0x40080
	v_lshl_add_u64 v[194:195], v[196:197], 0, s[64:65]
	s_addc_u32 s29, s29, 0
	s_add_i32 s30, s53, s39
	global_load_lds_dwordx4 v[194:195], off
	v_lshl_add_u64 v[194:195], s[28:29], 0, v[96:97]
	s_mov_b32 m0, s30
	s_nop 0
	global_load_lds_dwordx4 v[194:195], off
	v_lshl_add_u64 v[194:195], s[28:29], 0, v[202:203]
	s_add_i32 m0, s30, 0x2000
	s_nop 0
	global_load_lds_dwordx4 v[194:195], off
	v_lshl_add_u64 v[194:195], v[200:201], 0, s[64:65]
	s_mov_b32 m0, s45
	s_nop 0
	global_load_lds_dwordx4 v[194:195], off
	v_lshl_add_u64 v[194:195], v[212:213], 0, s[64:65]
	s_mov_b32 m0, s46
	s_nop 0
	global_load_lds_dwordx4 v[194:195], off
	s_waitcnt vmcnt(8)
	s_waitcnt lgkmcnt(0)
	s_barrier
	s_setprio 1
	s_waitcnt lgkmcnt(0)
	v_mfma_f32_16x16x32_bf16 v[60:63], v[122:125], v[162:165], v[60:63]
	v_mfma_f32_16x16x32_bf16 v[56:59], v[130:133], v[162:165], v[56:59]
	v_mfma_f32_16x16x32_bf16 v[44:47], v[122:125], v[170:173], v[44:47]
	v_mfma_f32_16x16x32_bf16 v[40:43], v[130:133], v[170:173], v[40:43]
	v_mfma_f32_16x16x32_bf16 v[28:31], v[122:125], v[178:181], v[28:31]
	v_mfma_f32_16x16x32_bf16 v[24:27], v[130:133], v[178:181], v[24:27]
	v_mfma_f32_16x16x32_bf16 v[12:15], v[122:125], v[186:189], v[12:15]
	v_mfma_f32_16x16x32_bf16 v[8:11], v[130:133], v[186:189], v[8:11]
	v_mfma_f32_16x16x32_bf16 v[60:63], v[126:129], v[166:169], v[60:63]
	v_mfma_f32_16x16x32_bf16 v[56:59], v[134:137], v[166:169], v[56:59]
	v_mfma_f32_16x16x32_bf16 v[44:47], v[126:129], v[174:177], v[44:47]
	v_mfma_f32_16x16x32_bf16 v[40:43], v[134:137], v[174:177], v[40:43]
	v_mfma_f32_16x16x32_bf16 v[28:31], v[126:129], v[182:185], v[28:31]
	v_mfma_f32_16x16x32_bf16 v[24:27], v[134:137], v[182:185], v[24:27]
	v_mfma_f32_16x16x32_bf16 v[12:15], v[126:129], v[208:211], v[12:15]
	v_mfma_f32_16x16x32_bf16 v[8:11], v[134:137], v[208:211], v[8:11]
	s_setprio 0
	s_setprio 1
	v_mfma_f32_16x16x32_bf16 v[52:55], v[138:141], v[162:165], v[52:55]
	v_mfma_f32_16x16x32_bf16 v[48:51], v[146:149], v[162:165], v[48:51]
	v_mfma_f32_16x16x32_bf16 v[36:39], v[138:141], v[170:173], v[36:39]
	v_mfma_f32_16x16x32_bf16 v[32:35], v[146:149], v[170:173], v[32:35]
	v_mfma_f32_16x16x32_bf16 v[20:23], v[138:141], v[178:181], v[20:23]
	v_mfma_f32_16x16x32_bf16 v[16:19], v[146:149], v[178:181], v[16:19]
	v_mfma_f32_16x16x32_bf16 v[4:7], v[138:141], v[186:189], v[4:7]
	v_mfma_f32_16x16x32_bf16 v[0:3], v[146:149], v[186:189], v[0:3]
	v_mfma_f32_16x16x32_bf16 v[52:55], v[142:145], v[166:169], v[52:55]
	v_mfma_f32_16x16x32_bf16 v[48:51], v[150:153], v[166:169], v[48:51]
	v_mfma_f32_16x16x32_bf16 v[36:39], v[142:145], v[174:177], v[36:39]
	v_mfma_f32_16x16x32_bf16 v[32:35], v[150:153], v[174:177], v[32:35]
	v_mfma_f32_16x16x32_bf16 v[20:23], v[142:145], v[182:185], v[20:23]
	v_mfma_f32_16x16x32_bf16 v[16:19], v[150:153], v[182:185], v[16:19]
	v_mfma_f32_16x16x32_bf16 v[4:7], v[142:145], v[208:211], v[4:7]
	v_mfma_f32_16x16x32_bf16 v[0:3], v[150:153], v[208:211], v[0:3]
	s_setprio 0
	s_barrier
	s_add_i32 s51, s51, 2
	s_add_u32 s26, s26, 0x100
	s_addc_u32 s27, s27, 0
	s_add_u32 s49, s49, 0x100
	s_addc_u32 s50, s50, 0
	s_cmp_gt_u32 s51, 13
	s_cbranch_scc1 .Lpeel_done_1237
